# pvprio + the counted lgkmcnt waits inside the prio-raised PV clusters merged into one lgkmcnt(0) (32 satisfied waits deleted)
# baseline (speedup 1.0000x reference)
; template <int MODE> ...
;     ...
;     auto body = [&](const int t) __attribute__((always_inline)) {
;         if (t >= act0 && t < act0 + actn) {
;         const LAS unsigned char* Sl = ring + ((t + base) % 3) * SLOT;
; #pragma unroll
;         for (int hf = 0; hf < NH; ++hf) {
;             if (MODE == 1) { const int ks = ktok0 + 64 * t + 32 * hf;
;                 if (ks + 31 < qtok0 - 128 || ks > qtok0 + 31 + 128) continue; }
;             bf16x8 kf[2][2][2];
; #pragma unroll
;             for (int jj = 0; jj < 2; ++jj)
; #pragma unroll
;                 for (int kt = 0; kt < 2; ++kt)
; #pragma unroll
;                     for (int ks = 0; ks < 2; ++ks) kf[jj][kt][ks] = *(const LAS bf16x8*)(Sl + kad[jj][ks] + (32 * hf + 16 * kt) * 128);
;             f32x4 bb[2][2];
; #pragma unroll
;             for (int jj = 0; jj < 2; ++jj) { const LAS f32x4* bl = bcp + ((MODE == 0) ? (dr0 + t - act0) * 8 : 16 * t + 8 * hf) + bofs[jj];
; #pragma unroll
;                 for (int kt = 0; kt < 2; ++kt) bb[jj][kt] = bl[4 * kt]; }
;             s16x4 vlo[2][4], vhi[2][4];
; #pragma unroll
;             for (int jj = 0; jj < 2; ++jj)
; #pragma unroll
;                 for (int dt = 0; dt < 4; ++dt) { const LAS unsigned char* vp = Sl + vad[jj] + (32 * hf) * 128 + ((dt ^ sv) << 5);
;                     vlo[jj][dt] = __builtin_bit_cast(s16x4, __builtin_amdgcn_ds_read_tr16_b64_v4i16((LAS s16x4*)(vp)));
;                     vhi[jj][dt] = __builtin_bit_cast(s16x4, __builtin_amdgcn_ds_read_tr16_b64_v4i16((LAS s16x4*)(vp + 2048))); }
;             __builtin_amdgcn_sched_barrier(0);
;             f32x4 s[2][2];
; #pragma unroll
;             for (int jj = 0; jj < 2; ++jj)
; #pragma unroll
;                 for (int kt = 0; kt < 2; ++kt) { f32x4 a = (MODE == 0) ? bb[jj][kt] + mneg[jj][kt] : bb[jj][kt];
;                     a = __builtin_amdgcn_mfma_f32_16x16x32_bf16(kf[jj][kt][0], qf[jj][0], a, 0, 0, 0);
;                     s[jj][kt] = __builtin_amdgcn_mfma_f32_16x16x32_bf16(kf[jj][kt][1], qf[jj][1], a, 0, 0, 0); }
;             u32x4 pw[2];
; #pragma unroll
;             for (int jj = 0; jj < 2; ++jj) {
;                 const float tm = vmax3(vmax3(s[jj][0][0], s[jj][0][1], s[jj][0][2]), vmax3(s[jj][0][3], s[jj][1][0], s[jj][1][1]), vmax3(s[jj][1][2], s[jj][1][3], s[jj][1][3]));
;                 const float mn = quad_max3(mrun[jj], tm);
.LBB0_278:
	s_sub_i32 s52, s25, s23
	v_lshlrev_b32_e32 v94, 5, v93
	s_add_i32 s0, s23, 7
	v_xor_b32_e32 v95, 32, v94
	v_xor_b32_e32 v96, 64, v94
	s_cmp_gt_u32 s0, 7
	v_xor_b32_e32 v97, 0x60, v94
	s_cbranch_scc1 .LBB0_291
	s_lshl_b32 s0, s86, 14
	s_add_i32 s0, s0, 0
	v_add_u32_e32 v0, s0, v89
	s_lshl_b32 s14, s52, 7
	v_add_u32_e32 v2, s0, v88
	ds_read_b128 v[6:9], v0
	ds_read_b128 v[10:13], v0 offset:2048
	ds_read_b128 v[14:17], v2
	ds_read_b128 v[34:37], v2 offset:2048
	v_add_u32_e32 v0, s0, v92
	s_add_i32 s14, s24, s14
	v_add_u32_e32 v2, s0, v91
	ds_read_b128 v[38:41], v0
	ds_read_b128 v[42:45], v0 offset:2048
	ds_read_b128 v[46:49], v2
	ds_read_b128 v[50:53], v2 offset:2048
	v_lshl_add_u32 v0, v87, 4, s14
	ds_read_b128 v[54:57], v0
	ds_read_b128 v[58:61], v0 offset:64
	v_lshl_add_u32 v0, v90, 4, s14
	ds_read_b128 v[62:65], v0
	ds_read_b128 v[66:69], v0 offset:64
	v_add3_u32 v0, v86, v122, s0
	v_add_u32_e32 v2, v0, v94
	v_add_u32_e32 v3, v0, v95
	ds_read_b64_tr_b16 v[70:71], v2 offset:8192
	ds_read_b64_tr_b16 v[72:73], v2 offset:10240
	ds_read_b64_tr_b16 v[74:75], v3 offset:8192
	ds_read_b64_tr_b16 v[76:77], v3 offset:10240
	v_add_u32_e32 v2, v0, v96
	v_add_u32_e32 v0, v0, v97
	ds_read_b64_tr_b16 v[78:79], v2 offset:8192
	ds_read_b64_tr_b16 v[80:81], v2 offset:10240
	ds_read_b64_tr_b16 v[126:127], v0 offset:8192
	ds_read_b64_tr_b16 v[128:129], v0 offset:10240
	v_add3_u32 v0, v123, v122, s0
	v_add_u32_e32 v2, v0, v94
	v_add_u32_e32 v3, v0, v95
	ds_read_b64_tr_b16 v[130:131], v2 offset:8192
	ds_read_b64_tr_b16 v[132:133], v2 offset:10240
	ds_read_b64_tr_b16 v[134:135], v3 offset:8192
	ds_read_b64_tr_b16 v[136:137], v3 offset:10240
	v_add_u32_e32 v2, v0, v96
	v_add_u32_e32 v0, v0, v97
	ds_read_b64_tr_b16 v[138:139], v2 offset:8192
	ds_read_b64_tr_b16 v[140:141], v2 offset:10240
	ds_read_b64_tr_b16 v[2:3], v0 offset:8192
	ds_read_b64_tr_b16 v[4:5], v0 offset:10240
	s_waitcnt lgkmcnt(14)
	v_pk_add_f32 v[56:57], v[112:113], v[56:57]
	v_pk_add_f32 v[54:55], v[110:111], v[54:55]
	s_mov_b32 s0, 0xf149f2ca
	s_nop 0
	v_mfma_f32_16x16x32_bf16 v[6:9], v[6:9], v[30:33], v[54:57]
	s_nop 2
	v_pk_add_f32 v[56:57], v[114:115], v[60:61]
	v_pk_add_f32 v[54:55], v[108:109], v[58:59]
	v_mfma_f32_16x16x32_bf16 v[6:9], v[14:17], v[26:29], v[6:9]
	v_pk_add_f32 v[16:17], v[106:107], v[64:65]
	v_pk_add_f32 v[14:15], v[102:103], v[62:63]
	v_mfma_f32_16x16x32_bf16 v[10:13], v[10:13], v[30:33], v[54:57]
	v_mfma_f32_16x16x32_bf16 v[10:13], v[34:37], v[26:29], v[10:13]
	s_nop 2
	v_maximum3_f32 v0, v6, v7, v8
	v_pk_add_f32 v[56:57], v[104:105], v[68:69]
	v_pk_add_f32 v[54:55], v[100:101], v[66:67]
	v_mfma_f32_16x16x32_bf16 v[14:17], v[38:41], v[22:25], v[14:17]
	v_mfma_f32_16x16x32_bf16 v[14:17], v[46:49], v[18:21], v[14:17]
	v_maximum3_f32 v34, v9, v10, v11
	v_maximum3_f32 v35, v12, v13, v13
	v_maximum3_f32 v0, v0, v34, v35
	v_mov_b32_e32 v34, v0
	s_nop 1
	v_permlane16_swap_b32_e32 v0, v34
	v_maximum3_f32 v0, v0, v34, v34
	v_mov_b32_e32 v34, v0
	s_nop 1
	v_permlane32_swap_b32_e32 v0, v34
	v_maximum3_f32 v125, v0, s0, v34
	v_mfma_f32_16x16x32_bf16 v[34:37], v[42:45], v[22:25], v[54:57]
	v_sub_f32_e32 v6, v6, v125
	v_exp_f32_e32 v38, v6
	v_sub_f32_e32 v6, v7, v125
	v_mfma_f32_16x16x32_bf16 v[34:37], v[50:53], v[18:21], v[34:37]
	v_exp_f32_e32 v40, v6
	v_sub_f32_e32 v6, v8, v125
	v_exp_f32_e32 v42, v6
	v_sub_f32_e32 v6, v9, v125
	v_sub_f32_e32 v0, 0xf149f2ca, v125
	v_exp_f32_e32 v66, v6
	v_sub_f32_e32 v6, v10, v125
	v_exp_f32_e32 v68, v6
	v_sub_f32_e32 v6, v11, v125
	v_exp_f32_e32 v146, v0
	v_maximum3_f32 v0, v14, v15, v16
	v_maximum3_f32 v10, v17, v34, v35
	v_maximum3_f32 v11, v36, v37, v37
	v_maximum3_f32 v0, v0, v10, v11
	v_mov_b32_e32 v10, v0
	s_nop 1
	v_permlane16_swap_b32_e32 v0, v10
	v_maximum3_f32 v0, v0, v10, v10
	v_mov_b32_e32 v10, v0
	s_nop 1
	v_permlane32_swap_b32_e32 v0, v10
	v_maximum3_f32 v124, v0, s0, v10
	v_exp_f32_e32 v98, v6
	v_sub_f32_e32 v6, v12, v125
	v_sub_f32_e32 v0, 0xf149f2ca, v124
	v_exp_f32_e32 v142, v6
	v_sub_f32_e32 v6, v13, v125
	v_sub_f32_e32 v10, v14, v124
	v_exp_f32_e32 v147, v0
	v_exp_f32_e32 v144, v6
	v_exp_f32_e32 v39, v10
	v_sub_f32_e32 v10, v15, v124
	v_exp_f32_e32 v41, v10
	v_sub_f32_e32 v10, v16, v124
	v_sub_f32_e32 v0, v34, v124
	v_exp_f32_e32 v43, v10
	v_sub_f32_e32 v10, v17, v124
	v_exp_f32_e32 v69, v0
	v_sub_f32_e32 v0, v35, v124
	v_exp_f32_e32 v67, v10
	v_pk_mul_f32 v[10:11], v[146:147], 0 op_sel_hi:[1,0]
	v_exp_f32_e32 v99, v0
	v_sub_f32_e32 v0, v36, v124
	v_cvt_pk_bf16_f32 v6, v38, v40
	v_cvt_pk_bf16_f32 v7, v42, v66
	v_cvt_pk_bf16_f32 v8, v68, v98
	v_cvt_pk_bf16_f32 v9, v142, v144
	v_mov_b32_e32 v14, v10
	v_mov_b32_e32 v15, v10
	v_mov_b32_e32 v16, v10
	v_mov_b32_e32 v17, v10
	v_exp_f32_e32 v143, v0
	v_sub_f32_e32 v0, v37, v124
	v_mfma_f32_16x16x32_bf16 v[54:57], v[70:73], v[6:9], v[14:17]
	v_exp_f32_e32 v145, v0
	v_mov_b32_e32 v10, v11
	v_mov_b32_e32 v12, v11
	s_setprio 1
	s_waitcnt lgkmcnt(0)
	v_mfma_f32_16x16x32_bf16 v[62:65], v[74:77], v[6:9], v[14:17]
	v_mov_b32_e32 v13, v11
	v_cvt_pk_bf16_f32 v34, v39, v41
	v_cvt_pk_bf16_f32 v35, v43, v67
	v_mfma_f32_16x16x32_bf16 v[58:61], v[78:81], v[6:9], v[14:17]
	v_cvt_pk_bf16_f32 v36, v69, v99
	v_cvt_pk_bf16_f32 v37, v143, v145
	v_mfma_f32_16x16x32_bf16 v[50:53], v[126:129], v[6:9], v[14:17]
	v_add_f32_e64 v6, v38, 0
	v_add_f32_e64 v7, v39, 0
	v_pk_add_f32 v[6:7], v[40:41], v[6:7]
	v_mfma_f32_16x16x32_bf16 v[46:49], v[130:133], v[34:37], v[10:13]
	v_pk_add_f32 v[6:7], v[42:43], v[6:7]
	v_pk_add_f32 v[6:7], v[66:67], v[6:7]
	v_mfma_f32_16x16x32_bf16 v[42:45], v[134:137], v[34:37], v[10:13]
	v_pk_add_f32 v[6:7], v[68:69], v[6:7]
	v_pk_add_f32 v[6:7], v[98:99], v[6:7]
	v_mfma_f32_16x16x32_bf16 v[38:41], v[138:141], v[34:37], v[10:13]
	v_pk_add_f32 v[6:7], v[142:143], v[6:7]
	v_pk_add_f32 v[6:7], v[144:145], v[6:7]
	v_mfma_f32_16x16x32_bf16 v[34:37], v[2:5], v[34:37], v[10:13]
	s_setprio 0
	v_fma_f32 v98, v146, 0, v6
	v_fma_f32 v99, v147, 0, v7
	s_cmp_eq_u32 s41, 1
	s_cbranch_scc1 .LBB0_281
	s_branch .LBB0_292

; #define GAS __attribute__((address_space(1)))
; #define DMA_TILE(t) do { const unsigned sl_ = (unsigned)__builtin_amdgcn_readfirstlane(ring0 + (unsigned)(((t) + base) % 3) * SLOT); \
;         glds16kv(loffk, loffv, kg + (size_t)(t) * 64 * PITCH, vg + (size_t)(t) * 64 * PITCH, sl_); } while (0)
; #define DMA_NEXT(i) do { const unsigned sl_ = (unsigned)__builtin_amdgcn_readfirstlane(ring0 + (unsigned)((nT + (i) + base) % 3) * SLOT); \
;         glds16kv(loffk, loffv, nK + (size_t)(i) * 64 * PITCH, nV + (size_t)(i) * 64 * PITCH, sl_); } while (0)
; template <int MODE> ...
;     ...
;     auto head = [&](const int t) __attribute__((always_inline)) {
;         if (t >= 2) { if (t + 1 < nT || nK) asm volatile("s_waitcnt vmcnt(2)" ::: "memory"); else asm volatile("s_waitcnt vmcnt(0)" ::: "memory"); }
;         __builtin_amdgcn_s_barrier();
;         if (t + 2 < nT) DMA_TILE(t + 2); else if (nK) DMA_NEXT(t + 2 - nT);
;     };
;     auto body = [&](const int t) __attribute__((always_inline)) {
;         if (t >= act0 && t < act0 + actn) {
;     ...
;     { const GAS bf16_t* qs = nQ ? (const GAS bf16_t*)nQ : (const GAS bf16_t*)proj + (size_t)qtok0 * NIN + qcol;
; #pragma unroll
;       for (int jj = 0; jj < 2; ++jj)
; #pragma unroll
;           for (int ks = 0; ks < 2; ++ks) qn[jj][ks] = *(const GAS bf16x8*)(qs + (size_t)(16 * jj) * NIN + 32 * ks + qoff); }
.LBB0_283:
	s_add_i32 s42, s86, s26
	s_add_i32 s0, s42, 1
	s_mul_hi_i32 s14, s0, 0x55555556
	s_lshr_b32 s15, s14, 31
	s_add_i32 s14, s14, s15
	s_mul_i32 s14, s14, 3
	s_sub_i32 s0, s0, s14
	s_lshl_b32 s0, s0, 14
	s_add_i32 s0, s0, s94
	s_add_u32 s34, s34, 0x48000
	s_addc_u32 s35, s35, 0
	s_add_u32 s30, s30, 0x48000
	s_barrier
	s_addc_u32 s31, s31, 0
	s_mov_b32 m0, s0
	s_nop 0
	global_load_lds_dwordx4 v84, s[34:35]
	s_add_u32 m0, m0, 0x2000
	s_nop 0
	global_load_lds_dwordx4 v85, s[30:31]
	v_lshl_add_u64 v[6:7], v[82:83], 1, s[38:39]
	global_load_dwordx4 v[2:5], v[6:7], off
	global_load_dwordx4 v[10:13], v[6:7], off offset:64
	v_add_co_u32_e32 v6, vcc, 0x12000, v6
	s_cmp_gt_u32 s40, s27
	s_nop 0
	v_addc_co_u32_e32 v7, vcc, 0, v7, vcc
	global_load_dwordx4 v[14:17], v[6:7], off
	s_nop 0
	global_load_dwordx4 v[6:9], v[6:7], off offset:64
	s_cselect_b64 s[30:31], -1, 0
	s_add_i32 s0, s23, 8
	s_cmp_le_i32 s26, s0
	s_cselect_b64 s[26:27], -1, 0
	s_and_b64 s[26:27], s[30:31], s[26:27]
	s_and_b64 vcc, exec, s[26:27]
	s_cbranch_vccz .LBB0_285
; #define LAS __attribute__((address_space(3)))
; template <int MODE> ...
;     ...
;             if (MODE == 1) { const int ks = ktok0 + 64 * t + 32 * hf;
;                 if (ks + 31 < qtok0 - 128 || ks > qtok0 + 31 + 128) continue; }
;             bf16x8 kf[2][2][2];
; #pragma unroll
;             for (int jj = 0; jj < 2; ++jj)
; #pragma unroll
;                 for (int kt = 0; kt < 2; ++kt)
; #pragma unroll
;                     for (int ks = 0; ks < 2; ++ks) kf[jj][kt][ks] = *(const LAS bf16x8*)(Sl + kad[jj][ks] + (32 * hf + 16 * kt) * 128);
;             f32x4 bb[2][2];
; #pragma unroll
;             for (int jj = 0; jj < 2; ++jj) { const LAS f32x4* bl = bcp + ((MODE == 0) ? (dr0 + t - act0) * 8 : 16 * t + 8 * hf) + bofs[jj];
; #pragma unroll
;                 for (int kt = 0; kt < 2; ++kt) bb[jj][kt] = bl[4 * kt]; }
;             s16x4 vlo[2][4], vhi[2][4];
; #pragma unroll
;             for (int jj = 0; jj < 2; ++jj)
; #pragma unroll
;                 for (int dt = 0; dt < 4; ++dt) { const LAS unsigned char* vp = Sl + vad[jj] + (32 * hf) * 128 + ((dt ^ sv) << 5);
;                     vlo[jj][dt] = __builtin_bit_cast(s16x4, __builtin_amdgcn_ds_read_tr16_b64_v4i16((LAS s16x4*)(vp)));
;                     vhi[jj][dt] = __builtin_bit_cast(s16x4, __builtin_amdgcn_ds_read_tr16_b64_v4i16((LAS s16x4*)(vp + 2048))); }
;             __builtin_amdgcn_sched_barrier(0);
;             f32x4 s[2][2];
; #pragma unroll
;             for (int jj = 0; jj < 2; ++jj)
; #pragma unroll
;                 for (int kt = 0; kt < 2; ++kt) { f32x4 a = (MODE == 0) ? bb[jj][kt] + mneg[jj][kt] : bb[jj][kt];
;                     a = __builtin_amdgcn_mfma_f32_16x16x32_bf16(kf[jj][kt][0], qf[jj][0], a, 0, 0, 0);
;                     s[jj][kt] = __builtin_amdgcn_mfma_f32_16x16x32_bf16(kf[jj][kt][1], qf[jj][1], a, 0, 0, 0); }
;             u32x4 pw[2];
; #pragma unroll
;             for (int jj = 0; jj < 2; ++jj) {
;                 const float tm = vmax3(vmax3(s[jj][0][0], s[jj][0][1], s[jj][0][2]), vmax3(s[jj][0][3], s[jj][1][0], s[jj][1][1]), vmax3(s[jj][1][2], s[jj][1][3], s[jj][1][3]));
;                 const float mn = quad_max3(mrun[jj], tm);
;                 const float alpha = __builtin_amdgcn_exp2f(mrun[jj] - mn);
;                 mrun[jj] = mn;
;                 float rsum = 0.f;
; #pragma unroll
;                 for (int kt = 0; kt < 2; ++kt)
; #pragma unroll
	s_add_i32 s0, s41, s86
	s_mul_hi_i32 s14, s0, 0x55555556
	s_lshr_b32 s15, s14, 31
	s_add_i32 s14, s14, s15
	s_mul_i32 s14, s14, 3
	s_sub_i32 s0, s0, s14
	s_lshl_b32 s0, s0, 14
	s_sub_i32 s14, s41, s23
	s_add_i32 s0, s0, 0
	s_add_i32 s14, s14, s25
	v_add_u32_e32 v0, s0, v89
	s_lshl_b32 s14, s14, 7
	v_add_u32_e32 v66, s0, v88
	ds_read_b128 v[126:129], v0
	ds_read_b128 v[130:133], v0 offset:2048
	ds_read_b128 v[134:137], v66
	ds_read_b128 v[138:141], v66 offset:2048
	v_add_u32_e32 v0, s0, v92
	s_add_i32 s24, s24, s14
	v_add_u32_e32 v66, s0, v91
	ds_read_b128 v[142:145], v0
	ds_read_b128 v[146:149], v0 offset:2048
	ds_read_b128 v[150:153], v66
	ds_read_b128 v[154:157], v66 offset:2048
	v_lshl_add_u32 v0, v87, 4, s24
	ds_read_b128 v[158:161], v0
	ds_read_b128 v[162:165], v0 offset:64
	v_lshl_add_u32 v0, v90, 4, s24
	ds_read_b128 v[166:169], v0
	ds_read_b128 v[170:173], v0 offset:64
	v_lshlrev_b32_e32 v0, 5, v93
	v_add3_u32 v66, v86, v122, s0
	v_add_u32_e32 v67, v66, v0
	v_xor_b32_e32 v68, 32, v0
	v_add_u32_e32 v69, v66, v68
	ds_read_b64_tr_b16 v[94:95], v67 offset:8192
	ds_read_b64_tr_b16 v[96:97], v67 offset:10240
	ds_read_b64_tr_b16 v[90:91], v69 offset:8192
	ds_read_b64_tr_b16 v[92:93], v69 offset:10240
	v_xor_b32_e32 v67, 64, v0
	v_xor_b32_e32 v70, 0x60, v0
	v_add_u32_e32 v69, v66, v67
	v_add_u32_e32 v66, v66, v70
	ds_read_b64_tr_b16 v[86:87], v69 offset:8192
	ds_read_b64_tr_b16 v[88:89], v69 offset:10240
	ds_read_b64_tr_b16 v[82:83], v66 offset:8192
	ds_read_b64_tr_b16 v[84:85], v66 offset:10240
	v_add3_u32 v66, v123, v122, s0
	v_add_u32_e32 v0, v66, v0
	v_add_u32_e32 v68, v66, v68
	ds_read_b64_tr_b16 v[78:79], v0 offset:8192
	ds_read_b64_tr_b16 v[80:81], v0 offset:10240
	ds_read_b64_tr_b16 v[74:75], v68 offset:8192
	ds_read_b64_tr_b16 v[76:77], v68 offset:10240
	v_add_u32_e32 v0, v66, v67
	v_add_u32_e32 v68, v66, v70
	ds_read_b64_tr_b16 v[70:71], v0 offset:8192
	ds_read_b64_tr_b16 v[72:73], v0 offset:10240
	ds_read_b64_tr_b16 v[66:67], v68 offset:8192
	ds_read_b64_tr_b16 v[68:69], v68 offset:10240
	s_waitcnt lgkmcnt(14)
	v_pk_add_f32 v[112:113], v[112:113], v[160:161]
	v_pk_add_f32 v[110:111], v[110:111], v[158:159]
	v_pk_add_f32 v[114:115], v[114:115], v[164:165]
	v_pk_add_f32 v[100:101], v[100:101], v[170:171]
	v_mfma_f32_16x16x32_bf16 v[110:113], v[126:129], v[30:33], v[110:113]
	v_mfma_f32_16x16x32_bf16 v[126:129], v[134:137], v[26:29], v[110:113]
	s_nop 6
	v_pk_add_f32 v[112:113], v[108:109], v[162:163]
	v_maximum3_f32 v0, v126, v127, v128
	v_pk_add_f32 v[108:109], v[106:107], v[168:169]
	v_mfma_f32_16x16x32_bf16 v[30:33], v[130:133], v[30:33], v[112:115]
	v_pk_add_f32 v[106:107], v[102:103], v[166:167]
	v_pk_add_f32 v[102:103], v[104:105], v[172:173]
	v_mfma_f32_16x16x32_bf16 v[26:29], v[138:141], v[26:29], v[30:33]
	s_nop 7
	v_maximum3_f32 v30, v129, v26, v27
	v_maximum3_f32 v31, v28, v29, v29
	v_maximum3_f32 v0, v0, v30, v31
	v_mov_b32_e32 v104, v0
	s_nop 1
	v_permlane16_swap_b32_e32 v0, v104
	v_mfma_f32_16x16x32_bf16 v[30:33], v[142:145], v[22:25], v[106:109]
	v_maximum3_f32 v0, v0, v104, v104
	v_mov_b32_e32 v104, v0
	s_nop 1
	v_permlane32_swap_b32_e32 v0, v104
	v_mfma_f32_16x16x32_bf16 v[22:25], v[146:149], v[22:25], v[100:103]
	v_maximum3_f32 v0, v125, v0, v104
	v_mfma_f32_16x16x32_bf16 v[30:33], v[150:153], v[18:21], v[30:33]
	s_nop 0
	v_sub_f32_e32 v100, v125, v0
	v_exp_f32_e32 v122, v100
	v_sub_f32_e32 v101, v126, v0
	v_mfma_f32_16x16x32_bf16 v[18:21], v[154:157], v[18:21], v[22:25]
	v_exp_f32_e32 v104, v101
	v_pk_mul_f32 v[60:61], v[60:61], v[122:123] op_sel_hi:[1,0]
	v_pk_mul_f32 v[58:59], v[58:59], v[122:123] op_sel_hi:[1,0]
	v_sub_f32_e32 v22, v127, v0
	v_exp_f32_e32 v106, v22
	v_sub_f32_e32 v22, v128, v0
	v_exp_f32_e32 v108, v22
	v_sub_f32_e32 v22, v129, v0
	v_exp_f32_e32 v110, v22
	v_sub_f32_e32 v22, v26, v0
	v_exp_f32_e32 v112, v22
	v_sub_f32_e32 v22, v27, v0
	v_exp_f32_e32 v114, v22
	v_sub_f32_e32 v22, v28, v0
	v_sub_f32_e32 v0, v29, v0
	v_exp_f32_e32 v126, v22
	v_exp_f32_e32 v128, v0
	v_pk_mul_f32 v[22:23], v[54:55], v[122:123] op_sel_hi:[1,0]
	v_maximum3_f32 v0, v30, v31, v32
	v_maximum3_f32 v54, v33, v18, v19
	v_maximum3_f32 v55, v20, v21, v21
	v_maximum3_f32 v0, v0, v54, v55
	v_mov_b32_e32 v54, v0
	s_nop 1
	v_permlane16_swap_b32_e32 v0, v54
	v_maximum3_f32 v0, v0, v54, v54
	v_mov_b32_e32 v54, v0
	s_nop 1
	v_permlane32_swap_b32_e32 v0, v54
	v_maximum3_f32 v0, v124, v0, v54
	v_sub_f32_e32 v30, v30, v0
	v_exp_f32_e32 v105, v30
	v_sub_f32_e32 v30, v31, v0
	v_exp_f32_e32 v107, v30
	v_sub_f32_e32 v30, v32, v0
	v_sub_f32_e32 v18, v18, v0
	v_exp_f32_e32 v109, v30
	v_sub_f32_e32 v30, v33, v0
	v_exp_f32_e32 v113, v18
	v_sub_f32_e32 v18, v19, v0
	v_sub_f32_e32 v54, v124, v0
	v_exp_f32_e32 v111, v30
	v_exp_f32_e32 v115, v18
	v_sub_f32_e32 v18, v20, v0
	v_pk_mul_f32 v[24:25], v[56:57], v[122:123] op_sel_hi:[1,0]
	v_pk_mul_f32 v[28:29], v[64:65], v[122:123] op_sel_hi:[1,0]
	v_pk_mul_f32 v[26:27], v[62:63], v[122:123] op_sel_hi:[1,0]
	v_pk_mul_f32 v[52:53], v[52:53], v[122:123] op_sel_hi:[1,0]
	v_pk_mul_f32 v[50:51], v[50:51], v[122:123] op_sel_hi:[1,0]
	v_exp_f32_e32 v127, v18
	v_sub_f32_e32 v0, v21, v0
	v_exp_f32_e32 v123, v54
	v_pk_add_f32 v[18:19], v[104:105], 0 op_sel_hi:[1,0]
	v_exp_f32_e32 v129, v0
	v_pk_add_f32 v[18:19], v[106:107], v[18:19]
	v_cvt_pk_bf16_f32 v100, v104, v106
	v_pk_add_f32 v[18:19], v[108:109], v[18:19]
	v_cvt_pk_bf16_f32 v101, v108, v110
	v_pk_add_f32 v[18:19], v[110:111], v[18:19]
	v_cvt_pk_bf16_f32 v102, v112, v114
	v_cvt_pk_bf16_f32 v103, v126, v128
	v_pk_add_f32 v[18:19], v[112:113], v[18:19]
	v_mov_b32_e32 v0, v123
	v_mfma_f32_16x16x32_bf16 v[54:57], v[94:97], v[100:103], v[22:25]
	v_pk_mul_f32 v[20:21], v[48:49], v[0:1] op_sel_hi:[1,0]
	s_setprio 1
	s_waitcnt lgkmcnt(0)
	v_mfma_f32_16x16x32_bf16 v[62:65], v[90:93], v[100:103], v[26:29]
	v_cvt_pk_bf16_f32 v22, v105, v107
	v_cvt_pk_bf16_f32 v23, v109, v111
	v_cvt_pk_bf16_f32 v24, v113, v115
	v_pk_add_f32 v[26:27], v[114:115], v[18:19]
	v_pk_mul_f32 v[18:19], v[46:47], v[0:1] op_sel_hi:[1,0]
	v_cvt_pk_bf16_f32 v25, v127, v129
	v_mfma_f32_16x16x32_bf16 v[58:61], v[86:89], v[100:103], v[58:61]
	v_pk_add_f32 v[26:27], v[126:127], v[26:27]
	v_pk_add_f32 v[26:27], v[128:129], v[26:27]
	v_mfma_f32_16x16x32_bf16 v[46:49], v[78:81], v[22:25], v[18:21]
	v_fma_f32 v98, v98, v122, v26
	v_fma_f32 v99, v99, v123, v27
	s_nop 0
	v_pk_mul_f32 v[20:21], v[44:45], v[0:1] op_sel_hi:[1,0]
	v_pk_mul_f32 v[18:19], v[42:43], v[0:1] op_sel_hi:[1,0]
	v_mfma_f32_16x16x32_bf16 v[50:53], v[82:85], v[100:103], v[50:53]
	v_mfma_f32_16x16x32_bf16 v[42:45], v[74:77], v[22:25], v[18:21]
	s_nop 2
	v_pk_mul_f32 v[20:21], v[40:41], v[0:1] op_sel_hi:[1,0]
	v_pk_mul_f32 v[18:19], v[38:39], v[0:1] op_sel_hi:[1,0]
	s_nop 0
	v_mfma_f32_16x16x32_bf16 v[38:41], v[70:73], v[22:25], v[18:21]
	s_nop 2
	v_pk_mul_f32 v[20:21], v[36:37], v[0:1] op_sel_hi:[1,0]
	v_pk_mul_f32 v[18:19], v[34:35], v[0:1] op_sel_hi:[1,0]
	s_setprio 0
	s_nop 0
	v_mfma_f32_16x16x32_bf16 v[34:37], v[66:69], v[22:25], v[18:21]

; #define LAS __attribute__((address_space(3)))
; template <int MODE> ...
;     ...
;             if (MODE == 1) { const int ks = ktok0 + 64 * t + 32 * hf;
;                 if (ks + 31 < qtok0 - 128 || ks > qtok0 + 31 + 128) continue; }
;             bf16x8 kf[2][2][2];
; #pragma unroll
;             for (int jj = 0; jj < 2; ++jj)
; #pragma unroll
;                 for (int kt = 0; kt < 2; ++kt)
; #pragma unroll
;                     for (int ks = 0; ks < 2; ++ks) kf[jj][kt][ks] = *(const LAS bf16x8*)(Sl + kad[jj][ks] + (32 * hf + 16 * kt) * 128);
;             f32x4 bb[2][2];
; #pragma unroll
;             for (int jj = 0; jj < 2; ++jj) { const LAS f32x4* bl = bcp + ((MODE == 0) ? (dr0 + t - act0) * 8 : 16 * t + 8 * hf) + bofs[jj];
; #pragma unroll
;                 for (int kt = 0; kt < 2; ++kt) bb[jj][kt] = bl[4 * kt]; }
;             s16x4 vlo[2][4], vhi[2][4];
; #pragma unroll
;             for (int jj = 0; jj < 2; ++jj)
; #pragma unroll
;                 for (int dt = 0; dt < 4; ++dt) { const LAS unsigned char* vp = Sl + vad[jj] + (32 * hf) * 128 + ((dt ^ sv) << 5);
;                     vlo[jj][dt] = __builtin_bit_cast(s16x4, __builtin_amdgcn_ds_read_tr16_b64_v4i16((LAS s16x4*)(vp)));
;                     vhi[jj][dt] = __builtin_bit_cast(s16x4, __builtin_amdgcn_ds_read_tr16_b64_v4i16((LAS s16x4*)(vp + 2048))); }
;             __builtin_amdgcn_sched_barrier(0);
;             f32x4 s[2][2];
; #pragma unroll
;             for (int jj = 0; jj < 2; ++jj)
; #pragma unroll
;                 for (int kt = 0; kt < 2; ++kt) { f32x4 a = (MODE == 0) ? bb[jj][kt] + mneg[jj][kt] : bb[jj][kt];
;                     a = __builtin_amdgcn_mfma_f32_16x16x32_bf16(kf[jj][kt][0], qf[jj][0], a, 0, 0, 0);
;                     s[jj][kt] = __builtin_amdgcn_mfma_f32_16x16x32_bf16(kf[jj][kt][1], qf[jj][1], a, 0, 0, 0); }
;             u32x4 pw[2];
; #pragma unroll
;             for (int jj = 0; jj < 2; ++jj) {
;                 const float tm = vmax3(vmax3(s[jj][0][0], s[jj][0][1], s[jj][0][2]), vmax3(s[jj][0][3], s[jj][1][0], s[jj][1][1]), vmax3(s[jj][1][2], s[jj][1][3], s[jj][1][3]));
;                 const float mn = quad_max3(mrun[jj], tm);
;                 const float alpha = __builtin_amdgcn_exp2f(mrun[jj] - mn);
;                 mrun[jj] = mn;
;                 float rsum = 0.f;
; #pragma unroll
;                 for (int kt = 0; kt < 2; ++kt)
; #pragma unroll
.LBB0_298:
	s_add_i32 s0, s86, 1
	s_mul_hi_i32 s14, s0, 0x55555556
	s_lshr_b32 s15, s14, 31
	s_add_i32 s14, s14, s15
	s_mul_i32 s14, s14, 3
	s_sub_i32 s0, s0, s14
	s_lshl_b32 s0, s0, 14
	s_add_i32 s0, s0, 0
	v_add_u32_e32 v0, s0, v89
	s_lshl_b32 s14, s52, 7
	v_add_u32_e32 v2, s0, v88
	ds_read_b128 v[126:129], v0
	ds_read_b128 v[130:133], v0 offset:2048
	ds_read_b128 v[134:137], v2
	ds_read_b128 v[138:141], v2 offset:2048
	v_add_u32_e32 v0, s0, v92
	s_add_i32 s14, s24, s14
	v_add_u32_e32 v2, s0, v91
	ds_read_b128 v[142:145], v0
	ds_read_b128 v[146:149], v0 offset:2048
	ds_read_b128 v[150:153], v2
	ds_read_b128 v[154:157], v2 offset:2048
	v_lshl_add_u32 v0, v87, 4, s14
	ds_read_b128 v[158:161], v0 offset:128
	ds_read_b128 v[162:165], v0 offset:192
	v_lshl_add_u32 v0, v90, 4, s14
	ds_read_b128 v[166:169], v0 offset:128
	ds_read_b128 v[170:173], v0 offset:192
	v_add3_u32 v0, v86, v122, s0
	v_add_u32_e32 v2, v0, v94
	v_add_u32_e32 v3, v0, v95
	ds_read_b64_tr_b16 v[78:79], v2 offset:8192
	ds_read_b64_tr_b16 v[80:81], v2 offset:10240
	ds_read_b64_tr_b16 v[74:75], v3 offset:8192
	ds_read_b64_tr_b16 v[76:77], v3 offset:10240
	v_add_u32_e32 v2, v0, v96
	v_add_u32_e32 v0, v0, v97
	ds_read_b64_tr_b16 v[70:71], v2 offset:8192
	ds_read_b64_tr_b16 v[72:73], v2 offset:10240
	ds_read_b64_tr_b16 v[66:67], v0 offset:8192
	ds_read_b64_tr_b16 v[68:69], v0 offset:10240
	v_add3_u32 v0, v123, v122, s0
	v_add_u32_e32 v2, v0, v94
	v_add_u32_e32 v3, v0, v95
	ds_read_b64_tr_b16 v[14:15], v2 offset:8192
	ds_read_b64_tr_b16 v[16:17], v2 offset:10240
	ds_read_b64_tr_b16 v[10:11], v3 offset:8192
	ds_read_b64_tr_b16 v[12:13], v3 offset:10240
	v_add_u32_e32 v2, v0, v96
	v_add_u32_e32 v0, v0, v97
	ds_read_b64_tr_b16 v[6:7], v2 offset:8192
	ds_read_b64_tr_b16 v[8:9], v2 offset:10240
	ds_read_b64_tr_b16 v[2:3], v0 offset:8192
	ds_read_b64_tr_b16 v[4:5], v0 offset:10240
	s_waitcnt lgkmcnt(14)
	v_pk_add_f32 v[160:161], v[112:113], v[160:161]
	v_pk_add_f32 v[158:159], v[110:111], v[158:159]
	s_nop 1
	v_mfma_f32_16x16x32_bf16 v[126:129], v[126:129], v[30:33], v[158:161]
	s_nop 2
	v_pk_add_f32 v[160:161], v[114:115], v[164:165]
	v_pk_add_f32 v[158:159], v[108:109], v[162:163]
	v_mfma_f32_16x16x32_bf16 v[126:129], v[134:137], v[26:29], v[126:129]
	v_pk_add_f32 v[136:137], v[106:107], v[168:169]
	v_pk_add_f32 v[134:135], v[102:103], v[166:167]
	v_mfma_f32_16x16x32_bf16 v[130:133], v[130:133], v[30:33], v[158:161]
	v_mfma_f32_16x16x32_bf16 v[130:133], v[138:141], v[26:29], v[130:133]
	s_nop 2
	v_maximum3_f32 v0, v126, v127, v128
	v_pk_add_f32 v[160:161], v[104:105], v[172:173]
	v_pk_add_f32 v[158:159], v[100:101], v[170:171]
	v_mfma_f32_16x16x32_bf16 v[134:137], v[142:145], v[22:25], v[134:137]
	v_mfma_f32_16x16x32_bf16 v[134:137], v[150:153], v[18:21], v[134:137]
	v_maximum3_f32 v138, v129, v130, v131
	v_maximum3_f32 v139, v132, v133, v133
	v_maximum3_f32 v0, v0, v138, v139
	v_mov_b32_e32 v138, v0
	s_nop 1
	v_permlane16_swap_b32_e32 v0, v138
	v_maximum3_f32 v0, v0, v138, v138
	v_mov_b32_e32 v138, v0
	s_nop 1
	v_permlane32_swap_b32_e32 v0, v138
	v_maximum3_f32 v162, v125, v0, v138
	v_mfma_f32_16x16x32_bf16 v[138:141], v[146:149], v[22:25], v[158:161]
	v_sub_f32_e32 v0, v125, v162
	v_sub_f32_e32 v125, v126, v162
	v_exp_f32_e32 v142, v125
	v_sub_f32_e32 v125, v127, v162
	v_exp_f32_e32 v144, v125
	v_sub_f32_e32 v125, v128, v162
	v_mfma_f32_16x16x32_bf16 v[138:141], v[154:157], v[18:21], v[138:141]
	v_exp_f32_e32 v146, v125
	v_sub_f32_e32 v125, v129, v162
	v_exp_f32_e32 v148, v125
	v_sub_f32_e32 v125, v130, v162
	v_exp_f32_e32 v130, v125
	v_sub_f32_e32 v125, v131, v162
	v_exp_f32_e32 v150, v125
	v_sub_f32_e32 v125, v132, v162
	v_exp_f32_e32 v132, v0
	v_sub_f32_e32 v0, v133, v162
	v_exp_f32_e32 v152, v125
	v_exp_f32_e32 v154, v0
	v_maximum3_f32 v0, v134, v135, v136
	v_maximum3_f32 v125, v137, v138, v139
	v_maximum3_f32 v129, v140, v141, v141
	v_maximum3_f32 v0, v0, v125, v129
	v_mov_b32_e32 v125, v0
	s_nop 1
	v_permlane16_swap_b32_e32 v0, v125
	v_maximum3_f32 v0, v0, v125, v125
	v_mov_b32_e32 v125, v0
	s_nop 1
	v_permlane32_swap_b32_e32 v0, v125
	v_maximum3_f32 v156, v124, v0, v125
	v_pk_mul_f32 v[56:57], v[56:57], v[132:133] op_sel_hi:[1,0]
	v_pk_mul_f32 v[54:55], v[54:55], v[132:133] op_sel_hi:[1,0]
	v_pk_mul_f32 v[64:65], v[64:65], v[132:133] op_sel_hi:[1,0]
	v_pk_mul_f32 v[62:63], v[62:63], v[132:133] op_sel_hi:[1,0]
	v_pk_mul_f32 v[60:61], v[60:61], v[132:133] op_sel_hi:[1,0]
	v_pk_mul_f32 v[58:59], v[58:59], v[132:133] op_sel_hi:[1,0]
	v_pk_mul_f32 v[52:53], v[52:53], v[132:133] op_sel_hi:[1,0]
	v_pk_mul_f32 v[50:51], v[50:51], v[132:133] op_sel_hi:[1,0]
	v_sub_f32_e32 v0, v134, v156
	v_sub_f32_e32 v133, v139, v156
	v_exp_f32_e32 v143, v0
	v_sub_f32_e32 v0, v135, v156
	v_sub_f32_e32 v131, v136, v156
	v_exp_f32_e32 v151, v133
	v_sub_f32_e32 v133, v140, v156
	v_exp_f32_e32 v145, v0
	v_sub_f32_e32 v0, v124, v156
	v_exp_f32_e32 v147, v131
	v_sub_f32_e32 v131, v137, v156
	v_exp_f32_e32 v153, v133
	v_sub_f32_e32 v133, v141, v156
	v_exp_f32_e32 v149, v131
	v_sub_f32_e32 v131, v138, v156
	v_exp_f32_e32 v155, v133
	v_exp_f32_e32 v133, v0
	v_exp_f32_e32 v131, v131
	v_cvt_pk_bf16_f32 v126, v142, v144
	v_cvt_pk_bf16_f32 v127, v146, v148
	v_cvt_pk_bf16_f32 v128, v130, v150
	v_cvt_pk_bf16_f32 v129, v152, v154
	v_pk_add_f32 v[124:125], v[142:143], 0 op_sel_hi:[1,0]
	v_mov_b32_e32 v0, v133
	v_pk_add_f32 v[124:125], v[144:145], v[124:125]
	s_setprio 1
	s_waitcnt lgkmcnt(0)
	v_mfma_f32_16x16x32_bf16 v[58:61], v[70:73], v[126:129], v[58:61]
	v_pk_mul_f32 v[48:49], v[48:49], v[0:1] op_sel_hi:[1,0]
	v_pk_mul_f32 v[46:47], v[46:47], v[0:1] op_sel_hi:[1,0]
	v_cvt_pk_bf16_f32 v70, v143, v145
	v_cvt_pk_bf16_f32 v71, v147, v149
	v_cvt_pk_bf16_f32 v72, v131, v151
	v_cvt_pk_bf16_f32 v73, v153, v155
	v_mfma_f32_16x16x32_bf16 v[54:57], v[78:81], v[126:129], v[54:57]
	v_pk_add_f32 v[78:79], v[146:147], v[124:125]
	v_pk_add_f32 v[78:79], v[148:149], v[78:79]
	v_mfma_f32_16x16x32_bf16 v[46:49], v[14:17], v[70:73], v[46:49]
	v_pk_mul_f32 v[16:17], v[44:45], v[0:1] op_sel_hi:[1,0]
	v_pk_mul_f32 v[14:15], v[42:43], v[0:1] op_sel_hi:[1,0]
	v_mfma_f32_16x16x32_bf16 v[62:65], v[74:77], v[126:129], v[62:65]
	v_pk_add_f32 v[74:75], v[130:131], v[78:79]
	v_pk_add_f32 v[74:75], v[150:151], v[74:75]
	v_mfma_f32_16x16x32_bf16 v[42:45], v[10:13], v[70:73], v[14:17]
	v_pk_mul_f32 v[12:13], v[40:41], v[0:1] op_sel_hi:[1,0]
	v_pk_mul_f32 v[10:11], v[38:39], v[0:1] op_sel_hi:[1,0]
	v_mfma_f32_16x16x32_bf16 v[50:53], v[66:69], v[126:129], v[50:53]
	v_pk_add_f32 v[66:67], v[152:153], v[74:75]
	v_pk_add_f32 v[14:15], v[154:155], v[66:67]
	v_mfma_f32_16x16x32_bf16 v[38:41], v[6:9], v[70:73], v[10:13]
	v_pk_mul_f32 v[8:9], v[36:37], v[0:1] op_sel_hi:[1,0]
	v_pk_mul_f32 v[6:7], v[34:35], v[0:1] op_sel_hi:[1,0]
	v_pk_fma_f32 v[98:99], v[98:99], v[132:133], v[14:15]
	v_mfma_f32_16x16x32_bf16 v[34:37], v[2:5], v[70:73], v[6:9]
	s_setprio 0
	v_mov_b32_e32 v125, v162
	v_mov_b32_e32 v124, v156
	s_cmp_eq_u32 s41, 2
	s_cbranch_scc1 .LBB0_281

; #define LAS __attribute__((address_space(3)))
; template <int MODE> ...
;     ...
;         if (t >= act0 && t < act0 + actn) {
;         const LAS unsigned char* Sl = ring + ((t + base) % 3) * SLOT;
; #pragma unroll
;         for (int hf = 0; hf < NH; ++hf) {
;             if (MODE == 1) { const int ks = ktok0 + 64 * t + 32 * hf;
;                 if (ks + 31 < qtok0 - 128 || ks > qtok0 + 31 + 128) continue; }
;             bf16x8 kf[2][2][2];
; #pragma unroll
;             for (int jj = 0; jj < 2; ++jj)
; #pragma unroll
;                 for (int kt = 0; kt < 2; ++kt)
; #pragma unroll
;                     for (int ks = 0; ks < 2; ++ks) kf[jj][kt][ks] = *(const LAS bf16x8*)(Sl + kad[jj][ks] + (32 * hf + 16 * kt) * 128);
;             f32x4 bb[2][2];
; #pragma unroll
;             for (int jj = 0; jj < 2; ++jj) { const LAS f32x4* bl = bcp + ((MODE == 0) ? (dr0 + t - act0) * 8 : 16 * t + 8 * hf) + bofs[jj];
; #pragma unroll
;                 for (int kt = 0; kt < 2; ++kt) bb[jj][kt] = bl[4 * kt]; }
;             s16x4 vlo[2][4], vhi[2][4];
; #pragma unroll
;             for (int jj = 0; jj < 2; ++jj)
; #pragma unroll
;                 for (int dt = 0; dt < 4; ++dt) { const LAS unsigned char* vp = Sl + vad[jj] + (32 * hf) * 128 + ((dt ^ sv) << 5);
;                     vlo[jj][dt] = __builtin_bit_cast(s16x4, __builtin_amdgcn_ds_read_tr16_b64_v4i16((LAS s16x4*)(vp)));
;                     vhi[jj][dt] = __builtin_bit_cast(s16x4, __builtin_amdgcn_ds_read_tr16_b64_v4i16((LAS s16x4*)(vp + 2048))); }
.LBB0_305:
	s_add_i32 s0, s65, 2
	s_cmp_ge_i32 s0, s23
	s_cselect_b64 s[60:61], -1, 0
	s_cmp_lt_i32 s0, s45
	s_cselect_b64 s[66:67], -1, 0
	s_and_b64 s[60:61], s[60:61], s[66:67]
	s_andn2_b64 vcc, exec, s[60:61]
	s_cbranch_vccnz .LBB0_300
	s_add_i32 s0, s86, s65
	s_add_i32 s0, s0, 2
	s_mul_hi_i32 s14, s0, 0x55555556
	s_lshr_b32 s15, s14, 31
	s_add_i32 s14, s14, s15
	s_mul_i32 s14, s14, 3
	s_sub_i32 s0, s0, s14
	s_lshl_b32 s0, s0, 14
	s_add_i32 s0, s0, 0
	v_add_u32_e32 v2, s0, v89
	v_add_u32_e32 v3, s0, v88
	ds_read_b128 v[130:133], v2
	ds_read_b128 v[134:137], v2 offset:2048
	ds_read_b128 v[138:141], v3
	ds_read_b128 v[142:145], v3 offset:2048
	v_add_u32_e32 v2, s0, v92
	v_add_u32_e32 v3, s0, v91
	ds_read_b128 v[146:149], v2
	ds_read_b128 v[150:153], v2 offset:2048
	ds_read_b128 v[154:157], v3
	ds_read_b128 v[158:161], v3 offset:2048
	v_add_u32_e32 v2, s50, v128
	v_add_u32_e32 v3, s50, v127
	ds_read_b128 v[162:165], v2
	ds_read_b128 v[166:169], v2 offset:64
	ds_read_b128 v[170:173], v3
	ds_read_b128 v[174:177], v3 offset:64
	v_add_u32_e32 v3, s0, v178
	v_add_u32_e32 v4, s0, v179
	ds_read_b64_tr_b16 v[78:79], v3 offset:8192
	ds_read_b64_tr_b16 v[80:81], v3 offset:10240
	ds_read_b64_tr_b16 v[74:75], v4 offset:8192
	ds_read_b64_tr_b16 v[76:77], v4 offset:10240
	v_add_u32_e32 v3, s0, v180
	v_add_u32_e32 v2, s0, v181
	ds_read_b64_tr_b16 v[70:71], v3 offset:8192
	ds_read_b64_tr_b16 v[72:73], v3 offset:10240
	ds_read_b64_tr_b16 v[66:67], v2 offset:8192
	ds_read_b64_tr_b16 v[68:69], v2 offset:10240
	v_add_u32_e32 v3, s0, v182
	v_add_u32_e32 v4, s0, v183
	ds_read_b64_tr_b16 v[14:15], v3 offset:8192
	ds_read_b64_tr_b16 v[16:17], v3 offset:10240
	ds_read_b64_tr_b16 v[10:11], v4 offset:8192
	ds_read_b64_tr_b16 v[12:13], v4 offset:10240
	v_add_u32_e32 v3, s0, v184
	v_add_u32_e32 v4, s0, v185
	ds_read_b64_tr_b16 v[6:7], v3 offset:8192
	ds_read_b64_tr_b16 v[8:9], v3 offset:10240
	ds_read_b64_tr_b16 v[2:3], v4 offset:8192
	ds_read_b64_tr_b16 v[4:5], v4 offset:10240
	s_waitcnt lgkmcnt(14)
; __device__ __forceinline__ unsigned cvtpk(float lo, float hi) { f32x2 v = {lo, hi}; bf16x2_t b = __builtin_convertvector(v, bf16x2_t); return __builtin_bit_cast(unsigned, b); }
; __device__ __forceinline__ float vmax3(float a, float b, float c) { return __builtin_elementwise_maximum(__builtin_elementwise_maximum(a, b), c); }
; template <int MODE> ...
;     ...
;             for (int jj = 0; jj < 2; ++jj)
; #pragma unroll
;                 for (int kt = 0; kt < 2; ++kt) { f32x4 a = (MODE == 0) ? bb[jj][kt] + mneg[jj][kt] : bb[jj][kt];
;                     a = __builtin_amdgcn_mfma_f32_16x16x32_bf16(kf[jj][kt][0], qf[jj][0], a, 0, 0, 0);
;                     s[jj][kt] = __builtin_amdgcn_mfma_f32_16x16x32_bf16(kf[jj][kt][1], qf[jj][1], a, 0, 0, 0); }
;             u32x4 pw[2];
; #pragma unroll
;             for (int jj = 0; jj < 2; ++jj) {
;                 const float tm = vmax3(vmax3(s[jj][0][0], s[jj][0][1], s[jj][0][2]), vmax3(s[jj][0][3], s[jj][1][0], s[jj][1][1]), vmax3(s[jj][1][2], s[jj][1][3], s[jj][1][3]));
;                 const float mn = quad_max3(mrun[jj], tm);
;                 const float alpha = __builtin_amdgcn_exp2f(mrun[jj] - mn);
;                 mrun[jj] = mn;
;                 float rsum = 0.f;
; #pragma unroll
;                 for (int kt = 0; kt < 2; ++kt)
; #pragma unroll
;                     for (int e = 0; e < 4; ++e) { s[jj][kt][e] = __builtin_amdgcn_exp2f(s[jj][kt][e] - mn); rsum += s[jj][kt][e]; }
;                 lrun[jj] = lrun[jj] * alpha + rsum;
; #pragma unroll
;                 for (int dt = 0; dt < 4; ++dt) o[jj][dt] *= alpha;
;                 pw[jj].x = cvtpk(s[jj][0][0], s[jj][0][1]); pw[jj].y = cvtpk(s[jj][0][2], s[jj][0][3]); pw[jj].z = cvtpk(s[jj][1][0], s[jj][1][1]); pw[jj].w = cvtpk(s[jj][1][2], s[jj][1][3]);
;             }
; #pragma unroll
;             for (int jj = 0; jj < 2; ++jj)
; #pragma unroll
;                 for (int dt = 0; dt < 4; ++dt) {
;                     const bf16x8 vf = (bf16x8){vlo[jj][dt][0], vlo[jj][dt][1], vlo[jj][dt][2], vlo[jj][dt][3], vhi[jj][dt][0], vhi[jj][dt][1], vhi[jj][dt][2], vhi[jj][dt][3]};
;                     o[jj][dt] = __builtin_amdgcn_mfma_f32_16x16x32_bf16(vf, __builtin_bit_cast(bf16x8, pw[jj]), o[jj][dt], 0, 0, 0); }
	v_pk_add_f32 v[164:165], v[112:113], v[164:165]
	v_pk_add_f32 v[162:163], v[110:111], v[162:163]
	s_nop 1
	v_mfma_f32_16x16x32_bf16 v[130:133], v[130:133], v[30:33], v[162:165]
	s_nop 2
	v_pk_add_f32 v[164:165], v[114:115], v[168:169]
	v_pk_add_f32 v[162:163], v[108:109], v[166:167]
	v_mfma_f32_16x16x32_bf16 v[130:133], v[138:141], v[26:29], v[130:133]
	v_pk_add_f32 v[140:141], v[106:107], v[172:173]
	v_pk_add_f32 v[138:139], v[102:103], v[170:171]
	v_mfma_f32_16x16x32_bf16 v[134:137], v[134:137], v[30:33], v[162:165]
	v_mfma_f32_16x16x32_bf16 v[134:137], v[142:145], v[26:29], v[134:137]
	s_nop 2
	v_maximum3_f32 v129, v130, v131, v132
	v_pk_add_f32 v[164:165], v[104:105], v[176:177]
	v_pk_add_f32 v[162:163], v[100:101], v[174:175]
	v_mfma_f32_16x16x32_bf16 v[138:141], v[146:149], v[22:25], v[138:141]
	v_mfma_f32_16x16x32_bf16 v[138:141], v[154:157], v[18:21], v[138:141]
	v_maximum3_f32 v142, v133, v134, v135
	v_maximum3_f32 v143, v136, v137, v137
	v_maximum3_f32 v129, v129, v142, v143
	v_mov_b32_e32 v142, v129
	s_nop 1
	v_permlane16_swap_b32_e32 v129, v142
	v_maximum3_f32 v129, v129, v142, v142
	v_mov_b32_e32 v142, v129
	s_nop 1
	v_permlane32_swap_b32_e32 v129, v142
	v_maximum3_f32 v129, v125, v129, v142
	v_mfma_f32_16x16x32_bf16 v[142:145], v[150:153], v[22:25], v[162:165]
	v_pk_add_f32 v[130:131], v[130:131], v[128:129] op_sel:[0,1] op_sel_hi:[1,1] neg_lo:[0,1] neg_hi:[0,1]
	v_pk_add_f32 v[132:133], v[132:133], v[128:129] op_sel:[0,1] op_sel_hi:[1,1] neg_lo:[0,1] neg_hi:[0,1]
	v_pk_add_f32 v[134:135], v[134:135], v[128:129] op_sel:[0,1] op_sel_hi:[1,1] neg_lo:[0,1] neg_hi:[0,1]
	v_pk_add_f32 v[136:137], v[136:137], v[128:129] op_sel:[0,1] op_sel_hi:[1,1] neg_lo:[0,1] neg_hi:[0,1]
	v_sub_f32_e32 v125, v125, v129
	v_mfma_f32_16x16x32_bf16 v[142:145], v[158:161], v[18:21], v[142:145]
	v_exp_f32_e32 v146, v130
	v_exp_f32_e32 v148, v131
	v_exp_f32_e32 v150, v132
	v_exp_f32_e32 v152, v133
	v_exp_f32_e32 v154, v135
	v_exp_f32_e32 v156, v136
	v_exp_f32_e32 v158, v137
	v_exp_f32_e32 v134, v134
	v_exp_f32_e32 v136, v125
	v_maximum3_f32 v125, v138, v139, v140
	v_maximum3_f32 v133, v141, v142, v143
	v_maximum3_f32 v135, v144, v145, v145
	v_maximum3_f32 v125, v125, v133, v135
	v_mov_b32_e32 v133, v125
	s_nop 1
	v_permlane16_swap_b32_e32 v125, v133
	v_maximum3_f32 v125, v125, v133, v133
	v_mov_b32_e32 v133, v125
	s_nop 1
	v_permlane32_swap_b32_e32 v125, v133
	v_maximum3_f32 v160, v124, v125, v133
	v_pk_add_f32 v[138:139], v[138:139], v[160:161] op_sel_hi:[1,0] neg_lo:[0,1] neg_hi:[0,1]
	v_pk_add_f32 v[140:141], v[140:141], v[160:161] op_sel_hi:[1,0] neg_lo:[0,1] neg_hi:[0,1]
	v_pk_add_f32 v[142:143], v[142:143], v[160:161] op_sel_hi:[1,0] neg_lo:[0,1] neg_hi:[0,1]
	v_pk_add_f32 v[144:145], v[144:145], v[160:161] op_sel_hi:[1,0] neg_lo:[0,1] neg_hi:[0,1]
	v_sub_f32_e32 v137, v124, v160
	v_exp_f32_e32 v147, v138
	v_pk_mul_f32 v[56:57], v[56:57], v[136:137] op_sel_hi:[1,0]
	v_exp_f32_e32 v149, v139
	v_pk_mul_f32 v[54:55], v[54:55], v[136:137] op_sel_hi:[1,0]
	v_exp_f32_e32 v151, v140
	v_pk_mul_f32 v[64:65], v[64:65], v[136:137] op_sel_hi:[1,0]
	v_exp_f32_e32 v153, v141
	v_pk_mul_f32 v[62:63], v[62:63], v[136:137] op_sel_hi:[1,0]
	v_exp_f32_e32 v155, v143
	v_pk_mul_f32 v[60:61], v[60:61], v[136:137] op_sel_hi:[1,0]
	v_exp_f32_e32 v157, v144
	v_pk_mul_f32 v[58:59], v[58:59], v[136:137] op_sel_hi:[1,0]
	v_exp_f32_e32 v159, v145
	v_pk_mul_f32 v[52:53], v[52:53], v[136:137] op_sel_hi:[1,0]
	v_exp_f32_e32 v135, v142
	v_pk_mul_f32 v[50:51], v[50:51], v[136:137] op_sel_hi:[1,0]
	v_exp_f32_e32 v137, v137
	v_cvt_pk_bf16_f32 v130, v146, v148
	v_cvt_pk_bf16_f32 v131, v150, v152
	v_cvt_pk_bf16_f32 v132, v134, v154
	v_cvt_pk_bf16_f32 v133, v156, v158
	s_setprio 1
	s_waitcnt lgkmcnt(0)
	v_mfma_f32_16x16x32_bf16 v[62:65], v[74:77], v[130:133], v[62:65]
	v_pk_add_f32 v[124:125], v[146:147], v[148:149]
	v_pk_mul_f32 v[48:49], v[48:49], v[136:137] op_sel:[0,1] op_sel_hi:[1,1]
	v_mfma_f32_16x16x32_bf16 v[58:61], v[70:73], v[130:133], v[58:61]
	v_pk_mul_f32 v[46:47], v[46:47], v[136:137] op_sel:[0,1] op_sel_hi:[1,1]
	v_cvt_pk_bf16_f32 v70, v147, v149
	v_cvt_pk_bf16_f32 v71, v151, v153
	v_cvt_pk_bf16_f32 v72, v135, v155
	v_cvt_pk_bf16_f32 v73, v157, v159
	v_mfma_f32_16x16x32_bf16 v[54:57], v[78:81], v[130:133], v[54:57]
	v_pk_add_f32 v[78:79], v[150:151], v[124:125]
	v_pk_add_f32 v[78:79], v[152:153], v[78:79]
	v_mfma_f32_16x16x32_bf16 v[46:49], v[14:17], v[70:73], v[46:49]
	v_pk_mul_f32 v[16:17], v[44:45], v[136:137] op_sel:[0,1] op_sel_hi:[1,1]
	v_pk_mul_f32 v[14:15], v[42:43], v[136:137] op_sel:[0,1] op_sel_hi:[1,1]
	v_pk_add_f32 v[74:75], v[134:135], v[78:79]
	v_mfma_f32_16x16x32_bf16 v[50:53], v[66:69], v[130:133], v[50:53]
	v_pk_add_f32 v[74:75], v[154:155], v[74:75]
	v_pk_add_f32 v[66:67], v[156:157], v[74:75]
	v_mfma_f32_16x16x32_bf16 v[42:45], v[10:13], v[70:73], v[14:17]
	v_pk_mul_f32 v[12:13], v[40:41], v[136:137] op_sel:[0,1] op_sel_hi:[1,1]
	v_pk_mul_f32 v[10:11], v[38:39], v[136:137] op_sel:[0,1] op_sel_hi:[1,1]
	v_pk_add_f32 v[14:15], v[158:159], v[66:67]
	v_mfma_f32_16x16x32_bf16 v[38:41], v[6:9], v[70:73], v[10:13]
	v_pk_mul_f32 v[8:9], v[36:37], v[136:137] op_sel:[0,1] op_sel_hi:[1,1]
	v_pk_mul_f32 v[6:7], v[34:35], v[136:137] op_sel:[0,1] op_sel_hi:[1,1]
	v_pk_fma_f32 v[98:99], v[98:99], v[136:137], v[14:15]
	v_mfma_f32_16x16x32_bf16 v[34:37], v[2:5], v[70:73], v[6:9]
	s_setprio 0
	v_mov_b32_e32 v125, v129
	v_mov_b32_e32 v124, v160
	s_branch .LBB0_300

; #define LAS __attribute__((address_space(3)))
; template <int MODE> ...
;     ...
;             if (MODE == 1) { const int ks = ktok0 + 64 * t + 32 * hf;
;                 if (ks + 31 < qtok0 - 128 || ks > qtok0 + 31 + 128) continue; }
;             bf16x8 kf[2][2][2];
; #pragma unroll
;             for (int jj = 0; jj < 2; ++jj)
; #pragma unroll
;                 for (int kt = 0; kt < 2; ++kt)
; #pragma unroll
;                     for (int ks = 0; ks < 2; ++ks) kf[jj][kt][ks] = *(const LAS bf16x8*)(Sl + kad[jj][ks] + (32 * hf + 16 * kt) * 128);
;             f32x4 bb[2][2];
; #pragma unroll
;             for (int jj = 0; jj < 2; ++jj) { const LAS f32x4* bl = bcp + ((MODE == 0) ? (dr0 + t - act0) * 8 : 16 * t + 8 * hf) + bofs[jj];
; #pragma unroll
;                 for (int kt = 0; kt < 2; ++kt) bb[jj][kt] = bl[4 * kt]; }
;             s16x4 vlo[2][4], vhi[2][4];
; #pragma unroll
;             for (int jj = 0; jj < 2; ++jj)
; #pragma unroll
;                 for (int dt = 0; dt < 4; ++dt) { const LAS unsigned char* vp = Sl + vad[jj] + (32 * hf) * 128 + ((dt ^ sv) << 5);
;                     vlo[jj][dt] = __builtin_bit_cast(s16x4, __builtin_amdgcn_ds_read_tr16_b64_v4i16((LAS s16x4*)(vp)));
;                     vhi[jj][dt] = __builtin_bit_cast(s16x4, __builtin_amdgcn_ds_read_tr16_b64_v4i16((LAS s16x4*)(vp + 2048))); }
;             __builtin_amdgcn_sched_barrier(0);
;             f32x4 s[2][2];
; #pragma unroll
;             for (int jj = 0; jj < 2; ++jj)
; #pragma unroll
;                 for (int kt = 0; kt < 2; ++kt) { f32x4 a = (MODE == 0) ? bb[jj][kt] + mneg[jj][kt] : bb[jj][kt];
;                     a = __builtin_amdgcn_mfma_f32_16x16x32_bf16(kf[jj][kt][0], qf[jj][0], a, 0, 0, 0);
;                     s[jj][kt] = __builtin_amdgcn_mfma_f32_16x16x32_bf16(kf[jj][kt][1], qf[jj][1], a, 0, 0, 0); }
;             u32x4 pw[2];
; #pragma unroll
;             for (int jj = 0; jj < 2; ++jj) {
;                 const float tm = vmax3(vmax3(s[jj][0][0], s[jj][0][1], s[jj][0][2]), vmax3(s[jj][0][3], s[jj][1][0], s[jj][1][1]), vmax3(s[jj][1][2], s[jj][1][3], s[jj][1][3]));
;                 const float mn = quad_max3(mrun[jj], tm);
;                 const float alpha = __builtin_amdgcn_exp2f(mrun[jj] - mn);
;                 mrun[jj] = mn;
;                 float rsum = 0.f;
; #pragma unroll
;                 for (int kt = 0; kt < 2; ++kt)
; #pragma unroll
.LBB0_343:
	s_add_i32 s0, s86, s65
	s_mul_hi_i32 s14, s0, 0x55555556
	s_lshr_b32 s15, s14, 31
	s_add_i32 s14, s14, s15
	s_mul_i32 s14, s14, 3
	s_sub_i32 s0, s0, s14
	s_lshl_b32 s0, s0, 14
	s_add_i32 s0, s0, 0
	s_add_i32 s14, s27, 31
	s_cmp_lt_i32 s14, s41
	s_cselect_b64 s[50:51], -1, 0
	s_cmp_gt_i32 s27, s45
	s_cselect_b64 s[52:53], -1, 0
	s_or_b64 s[50:51], s[50:51], s[52:53]
	v_add_u32_e32 v0, s0, v78
	s_and_b64 vcc, exec, s[50:51]
	v_add_u32_e32 v98, s0, v70
	v_add_u32_e32 v97, s0, v71
	v_add_u32_e32 v96, s40, v80
	v_add_u32_e32 v85, s40, v79
	v_add_u32_e32 v84, v0, v74
	v_add_u32_e32 v83, v0, v75
	v_add_u32_e32 v81, v0, v76
	v_add_u32_e32 v0, v0, v77
	s_cbranch_vccnz .LBB0_345
	v_add_u32_e32 v2, 0x10000, v96
	v_add_u32_e32 v3, 0x10040, v96
	ds_read_b128 v[100:103], v98
	ds_read_b128 v[104:107], v98 offset:2048
	ds_read_b128 v[108:111], v97
	ds_read_b128 v[112:115], v97 offset:2048
	ds_read_b128 v[118:121], v2
	ds_read_b128 v[122:125], v3
	v_add_u32_e32 v2, 0x10000, v85
	v_add_u32_e32 v3, 0x10040, v85
	ds_read_b128 v[126:129], v2
	ds_read_b128 v[130:133], v3
	ds_read_b64_tr_b16 v[14:15], v84 offset:8192
	ds_read_b64_tr_b16 v[16:17], v84 offset:10240
	ds_read_b64_tr_b16 v[10:11], v83 offset:8192
	ds_read_b64_tr_b16 v[12:13], v83 offset:10240
	ds_read_b64_tr_b16 v[6:7], v81 offset:8192
	ds_read_b64_tr_b16 v[8:9], v81 offset:10240
	ds_read_b64_tr_b16 v[2:3], v0 offset:8192
	ds_read_b64_tr_b16 v[4:5], v0 offset:10240
	s_waitcnt lgkmcnt(11)
	v_mfma_f32_16x16x32_bf16 v[118:121], v[100:103], v[30:33], v[118:121]
	s_waitcnt lgkmcnt(10)
	v_mfma_f32_16x16x32_bf16 v[122:125], v[104:107], v[30:33], v[122:125]
	v_mfma_f32_16x16x32_bf16 v[118:121], v[108:111], v[26:29], v[118:121]
	v_mfma_f32_16x16x32_bf16 v[122:125], v[112:115], v[26:29], v[122:125]
	s_waitcnt lgkmcnt(9)
	v_mfma_f32_16x16x32_bf16 v[100:103], v[100:103], v[22:25], v[126:129]
	s_nop 4
	v_maximum3_f32 v99, v118, v119, v120
	v_mfma_f32_16x16x32_bf16 v[100:103], v[108:111], v[18:21], v[100:103]
	v_maximum3_f32 v108, v121, v122, v123
	v_maximum3_f32 v109, v124, v125, v125
	v_maximum3_f32 v99, v99, v108, v109
	s_waitcnt lgkmcnt(8)
	v_mfma_f32_16x16x32_bf16 v[104:107], v[104:107], v[22:25], v[130:133]
	v_mov_b32_e32 v108, v99
	s_nop 1
	v_permlane16_swap_b32_e32 v99, v108
	v_maximum3_f32 v99, v99, v108, v108
	v_mfma_f32_16x16x32_bf16 v[104:107], v[112:115], v[18:21], v[104:107]
	v_mov_b32_e32 v108, v99
	s_nop 1
	v_permlane32_swap_b32_e32 v99, v108
	v_maximum3_f32 v99, v82, v99, v108
	v_sub_f32_e32 v82, v82, v99
	v_exp_f32_e32 v130, v82
	v_maximum3_f32 v82, v100, v101, v102
	v_maximum3_f32 v113, v103, v104, v105
	v_maximum3_f32 v115, v106, v107, v107
	v_maximum3_f32 v82, v82, v113, v115
	v_mov_b32_e32 v113, v82
	s_nop 1
	v_permlane16_swap_b32_e32 v82, v113
	v_maximum3_f32 v82, v82, v113, v113
	v_mov_b32_e32 v113, v82
	s_nop 1
	v_permlane32_swap_b32_e32 v82, v113
	v_maximum3_f32 v117, v95, v82, v113
	v_sub_f32_e32 v108, v118, v99
	v_sub_f32_e32 v82, v95, v117
	v_sub_f32_e32 v95, v100, v117
	v_exp_f32_e32 v112, v108
	v_sub_f32_e32 v108, v119, v99
	v_exp_f32_e32 v113, v95
	v_sub_f32_e32 v95, v101, v117
	v_exp_f32_e32 v114, v108
	v_sub_f32_e32 v108, v120, v99
	v_exp_f32_e32 v115, v95
	v_sub_f32_e32 v95, v102, v117
	v_exp_f32_e32 v118, v108
	v_sub_f32_e32 v108, v121, v99
	v_exp_f32_e32 v119, v95
	v_sub_f32_e32 v95, v103, v117
	v_exp_f32_e32 v120, v108
	v_sub_f32_e32 v108, v122, v99
	v_exp_f32_e32 v121, v95
	v_sub_f32_e32 v95, v104, v117
	v_exp_f32_e32 v122, v108
	v_sub_f32_e32 v108, v123, v99
	v_exp_f32_e32 v123, v95
	v_sub_f32_e32 v95, v105, v117
	v_pk_add_f32 v[100:101], v[112:113], 0 op_sel_hi:[1,0]
	v_exp_f32_e32 v126, v108
	v_sub_f32_e32 v108, v124, v99
	v_exp_f32_e32 v127, v95
	v_sub_f32_e32 v95, v106, v117
	v_pk_add_f32 v[100:101], v[114:115], v[100:101]
	v_exp_f32_e32 v124, v108
	v_sub_f32_e32 v108, v125, v99
	v_exp_f32_e32 v125, v95
	v_sub_f32_e32 v95, v107, v117
	v_pk_add_f32 v[100:101], v[118:119], v[100:101]
	v_exp_f32_e32 v128, v108
	v_pk_mul_f32 v[52:53], v[52:53], v[130:131] op_sel_hi:[1,0]
	v_pk_mul_f32 v[50:51], v[50:51], v[130:131] op_sel_hi:[1,0]
	v_pk_mul_f32 v[56:57], v[56:57], v[130:131] op_sel_hi:[1,0]
	v_pk_mul_f32 v[54:55], v[54:55], v[130:131] op_sel_hi:[1,0]
	v_pk_mul_f32 v[60:61], v[60:61], v[130:131] op_sel_hi:[1,0]
	v_pk_mul_f32 v[58:59], v[58:59], v[130:131] op_sel_hi:[1,0]
	v_pk_mul_f32 v[64:65], v[64:65], v[130:131] op_sel_hi:[1,0]
	v_pk_mul_f32 v[62:63], v[62:63], v[130:131] op_sel_hi:[1,0]
	v_exp_f32_e32 v129, v95
	v_pk_add_f32 v[100:101], v[120:121], v[100:101]
	v_exp_f32_e32 v131, v82
	v_pk_add_f32 v[100:101], v[122:123], v[100:101]
	v_cvt_pk_bf16_f32 v108, v112, v114
	v_pk_add_f32 v[100:101], v[126:127], v[100:101]
	v_mov_b32_e32 v82, v131
	v_pk_add_f32 v[100:101], v[124:125], v[100:101]
	v_cvt_pk_bf16_f32 v109, v118, v120
	v_pk_add_f32 v[100:101], v[128:129], v[100:101]
	v_cvt_pk_bf16_f32 v110, v122, v126
	v_cvt_pk_bf16_f32 v111, v124, v128
	v_pk_fma_f32 v[88:89], v[88:89], v[130:131], v[100:101]
	v_pk_mul_f32 v[36:37], v[36:37], v[82:83] op_sel_hi:[1,0]
	v_pk_mul_f32 v[34:35], v[34:35], v[82:83] op_sel_hi:[1,0]
	v_pk_mul_f32 v[40:41], v[40:41], v[82:83] op_sel_hi:[1,0]
	v_pk_mul_f32 v[38:39], v[38:39], v[82:83] op_sel_hi:[1,0]
	v_pk_mul_f32 v[44:45], v[44:45], v[82:83] op_sel_hi:[1,0]
	v_pk_mul_f32 v[42:43], v[42:43], v[82:83] op_sel_hi:[1,0]
	v_pk_mul_f32 v[48:49], v[48:49], v[82:83] op_sel_hi:[1,0]
	v_pk_mul_f32 v[46:47], v[46:47], v[82:83] op_sel_hi:[1,0]
	v_cvt_pk_bf16_f32 v100, v113, v115
	v_cvt_pk_bf16_f32 v101, v119, v121
	v_cvt_pk_bf16_f32 v102, v123, v127
	v_cvt_pk_bf16_f32 v103, v125, v129
	s_setprio 1
	s_waitcnt lgkmcnt(0)
	v_mfma_f32_16x16x32_bf16 v[50:53], v[14:17], v[108:111], v[50:53]
	v_mfma_f32_16x16x32_bf16 v[54:57], v[10:13], v[108:111], v[54:57]
	v_mfma_f32_16x16x32_bf16 v[58:61], v[6:9], v[108:111], v[58:61]
	v_mfma_f32_16x16x32_bf16 v[62:65], v[2:5], v[108:111], v[62:65]
	v_mfma_f32_16x16x32_bf16 v[34:37], v[14:17], v[100:103], v[34:37]
	v_mfma_f32_16x16x32_bf16 v[38:41], v[10:13], v[100:103], v[38:41]
	v_mfma_f32_16x16x32_bf16 v[42:45], v[6:9], v[100:103], v[42:45]
	v_mfma_f32_16x16x32_bf16 v[46:49], v[2:5], v[100:103], v[46:49]
	s_setprio 0
	v_mov_b32_e32 v82, v99
	v_mov_b32_e32 v95, v117
; #define LAS __attribute__((address_space(3)))
; template <int MODE> ...
;     ...
;             if (MODE == 1) { const int ks = ktok0 + 64 * t + 32 * hf;
;                 if (ks + 31 < qtok0 - 128 || ks > qtok0 + 31 + 128) continue; }
;             bf16x8 kf[2][2][2];
; #pragma unroll
;             for (int jj = 0; jj < 2; ++jj)
; #pragma unroll
;                 for (int kt = 0; kt < 2; ++kt)
; #pragma unroll
;                     for (int ks = 0; ks < 2; ++ks) kf[jj][kt][ks] = *(const LAS bf16x8*)(Sl + kad[jj][ks] + (32 * hf + 16 * kt) * 128);
;             f32x4 bb[2][2];
; #pragma unroll
;             for (int jj = 0; jj < 2; ++jj) { const LAS f32x4* bl = bcp + ((MODE == 0) ? (dr0 + t - act0) * 8 : 16 * t + 8 * hf) + bofs[jj];
; #pragma unroll
;                 for (int kt = 0; kt < 2; ++kt) bb[jj][kt] = bl[4 * kt]; }
;             s16x4 vlo[2][4], vhi[2][4];
; #pragma unroll
;             for (int jj = 0; jj < 2; ++jj)
; #pragma unroll
;                 for (int dt = 0; dt < 4; ++dt) { const LAS unsigned char* vp = Sl + vad[jj] + (32 * hf) * 128 + ((dt ^ sv) << 5);
;                     vlo[jj][dt] = __builtin_bit_cast(s16x4, __builtin_amdgcn_ds_read_tr16_b64_v4i16((LAS s16x4*)(vp)));
;                     vhi[jj][dt] = __builtin_bit_cast(s16x4, __builtin_amdgcn_ds_read_tr16_b64_v4i16((LAS s16x4*)(vp + 2048))); }
;             __builtin_amdgcn_sched_barrier(0);
;             f32x4 s[2][2];
; #pragma unroll
;             for (int jj = 0; jj < 2; ++jj)
; #pragma unroll
;                 for (int kt = 0; kt < 2; ++kt) { f32x4 a = (MODE == 0) ? bb[jj][kt] + mneg[jj][kt] : bb[jj][kt];
;                     a = __builtin_amdgcn_mfma_f32_16x16x32_bf16(kf[jj][kt][0], qf[jj][0], a, 0, 0, 0);
;                     s[jj][kt] = __builtin_amdgcn_mfma_f32_16x16x32_bf16(kf[jj][kt][1], qf[jj][1], a, 0, 0, 0); }
;             u32x4 pw[2];
; #pragma unroll
;             for (int jj = 0; jj < 2; ++jj) {
;                 const float tm = vmax3(vmax3(s[jj][0][0], s[jj][0][1], s[jj][0][2]), vmax3(s[jj][0][3], s[jj][1][0], s[jj][1][1]), vmax3(s[jj][1][2], s[jj][1][3], s[jj][1][3]));
;                 const float mn = quad_max3(mrun[jj], tm);
;                 const float alpha = __builtin_amdgcn_exp2f(mrun[jj] - mn);
;                 mrun[jj] = mn;
;                 float rsum = 0.f;
; #pragma unroll
;                 for (int kt = 0; kt < 2; ++kt)
; #pragma unroll
.LBB0_345:
	s_add_i32 s0, s27, 32
	s_add_i32 s14, s27, 63
	s_cmp_lt_i32 s14, s41
	s_cselect_b64 s[50:51], -1, 0
	s_cmp_gt_i32 s0, s45
	s_cselect_b64 s[52:53], -1, 0
	s_or_b64 s[50:51], s[50:51], s[52:53]
	s_and_b64 vcc, exec, s[50:51]
	s_cbranch_vccnz .LBB0_333
	v_add_u32_e32 v2, 0x10080, v96
	v_add_u32_e32 v3, 0x100c0, v96
	ds_read_b128 v[100:103], v98 offset:4096
	ds_read_b128 v[104:107], v98 offset:6144
	ds_read_b128 v[108:111], v97 offset:4096
	ds_read_b128 v[112:115], v97 offset:6144
	ds_read_b128 v[96:99], v2
	ds_read_b128 v[118:121], v3
	v_add_u32_e32 v2, 0x10080, v85
	v_add_u32_e32 v3, 0x100c0, v85
	ds_read_b128 v[122:125], v2
	ds_read_b128 v[126:129], v3
	ds_read_b64_tr_b16 v[14:15], v84 offset:12288
	ds_read_b64_tr_b16 v[16:17], v84 offset:14336
	ds_read_b64_tr_b16 v[10:11], v83 offset:12288
	ds_read_b64_tr_b16 v[12:13], v83 offset:14336
	ds_read_b64_tr_b16 v[6:7], v81 offset:12288
	ds_read_b64_tr_b16 v[8:9], v81 offset:14336
	ds_read_b64_tr_b16 v[2:3], v0 offset:12288
	ds_read_b64_tr_b16 v[4:5], v0 offset:14336
	s_waitcnt lgkmcnt(11)
	v_mfma_f32_16x16x32_bf16 v[96:99], v[100:103], v[30:33], v[96:99]
	s_waitcnt lgkmcnt(10)
	v_mfma_f32_16x16x32_bf16 v[118:121], v[104:107], v[30:33], v[118:121]
	v_mfma_f32_16x16x32_bf16 v[96:99], v[108:111], v[26:29], v[96:99]
	v_mfma_f32_16x16x32_bf16 v[118:121], v[112:115], v[26:29], v[118:121]
	s_waitcnt lgkmcnt(9)
	v_mfma_f32_16x16x32_bf16 v[100:103], v[100:103], v[22:25], v[122:125]
	s_nop 4
	v_maximum3_f32 v0, v96, v97, v98
	v_maximum3_f32 v81, v99, v118, v119
	v_maximum3_f32 v83, v120, v121, v121
	v_maximum3_f32 v0, v0, v81, v83
	v_mov_b32_e32 v81, v0
	s_waitcnt lgkmcnt(8)
	v_mfma_f32_16x16x32_bf16 v[104:107], v[104:107], v[22:25], v[126:129]
	v_permlane16_swap_b32_e32 v0, v81
	v_maximum3_f32 v0, v0, v81, v81
	v_mov_b32_e32 v81, v0
	s_nop 1
	v_permlane32_swap_b32_e32 v0, v81
	v_mfma_f32_16x16x32_bf16 v[100:103], v[108:111], v[18:21], v[100:103]
	v_maximum3_f32 v81, v82, v0, v81
	v_sub_f32_e32 v0, v82, v81
	v_sub_f32_e32 v82, v96, v81
	v_mfma_f32_16x16x32_bf16 v[104:107], v[112:115], v[18:21], v[104:107]
	v_exp_f32_e32 v96, v82
	v_sub_f32_e32 v82, v97, v81
	v_exp_f32_e32 v108, v82
	v_sub_f32_e32 v82, v98, v81
	v_exp_f32_e32 v98, v82
	v_sub_f32_e32 v82, v99, v81
	v_exp_f32_e32 v122, v0
	v_maximum3_f32 v0, v100, v101, v102
	v_maximum3_f32 v97, v103, v104, v105
	v_maximum3_f32 v99, v106, v107, v107
	v_maximum3_f32 v0, v0, v97, v99
	v_mov_b32_e32 v97, v0
	s_nop 1
	v_permlane16_swap_b32_e32 v0, v97
	v_maximum3_f32 v0, v0, v97, v97
	v_mov_b32_e32 v97, v0
	s_nop 1
	v_permlane32_swap_b32_e32 v0, v97
	v_maximum3_f32 v117, v95, v0, v97
	v_sub_f32_e32 v0, v95, v117
	v_sub_f32_e32 v95, v100, v117
	v_exp_f32_e32 v97, v95
	v_sub_f32_e32 v95, v101, v117
	v_exp_f32_e32 v109, v95
	v_sub_f32_e32 v95, v102, v117
	v_exp_f32_e32 v99, v95
	v_sub_f32_e32 v95, v103, v117
	v_exp_f32_e32 v110, v82
	v_sub_f32_e32 v82, v118, v81
	v_exp_f32_e32 v111, v95
	v_sub_f32_e32 v95, v104, v117
	v_exp_f32_e32 v112, v82
	v_sub_f32_e32 v82, v119, v81
	v_exp_f32_e32 v113, v95
	v_sub_f32_e32 v95, v105, v117
	v_exp_f32_e32 v114, v82
	v_sub_f32_e32 v82, v120, v81
	v_exp_f32_e32 v115, v95
	v_sub_f32_e32 v95, v106, v117
	v_exp_f32_e32 v118, v82
	v_sub_f32_e32 v82, v121, v81
	v_pk_mul_f32 v[52:53], v[52:53], v[122:123] op_sel_hi:[1,0]
	v_pk_mul_f32 v[50:51], v[50:51], v[122:123] op_sel_hi:[1,0]
	v_pk_mul_f32 v[56:57], v[56:57], v[122:123] op_sel_hi:[1,0]
	v_pk_mul_f32 v[54:55], v[54:55], v[122:123] op_sel_hi:[1,0]
	v_pk_mul_f32 v[60:61], v[60:61], v[122:123] op_sel_hi:[1,0]
	v_pk_mul_f32 v[58:59], v[58:59], v[122:123] op_sel_hi:[1,0]
	v_pk_mul_f32 v[64:65], v[64:65], v[122:123] op_sel_hi:[1,0]
	v_pk_mul_f32 v[62:63], v[62:63], v[122:123] op_sel_hi:[1,0]
	v_exp_f32_e32 v119, v95
	v_sub_f32_e32 v95, v107, v117
	v_exp_f32_e32 v123, v0
	v_exp_f32_e32 v120, v82
	v_pk_add_f32 v[100:101], v[96:97], 0 op_sel_hi:[1,0]
	v_exp_f32_e32 v121, v95
	v_pk_add_f32 v[100:101], v[108:109], v[100:101]
	v_mov_b32_e32 v0, v123
	v_pk_add_f32 v[100:101], v[98:99], v[100:101]
	v_cvt_pk_bf16_f32 v82, v96, v108
	v_pk_add_f32 v[100:101], v[110:111], v[100:101]
	v_cvt_pk_bf16_f32 v83, v98, v110
	v_cvt_pk_bf16_f32 v84, v112, v114
	v_cvt_pk_bf16_f32 v85, v118, v120
	v_pk_add_f32 v[100:101], v[112:113], v[100:101]
	v_pk_mul_f32 v[36:37], v[36:37], v[0:1] op_sel_hi:[1,0]
	v_pk_mul_f32 v[34:35], v[34:35], v[0:1] op_sel_hi:[1,0]
	v_pk_mul_f32 v[40:41], v[40:41], v[0:1] op_sel_hi:[1,0]
	v_pk_mul_f32 v[38:39], v[38:39], v[0:1] op_sel_hi:[1,0]
	v_pk_mul_f32 v[44:45], v[44:45], v[0:1] op_sel_hi:[1,0]
	v_pk_mul_f32 v[42:43], v[42:43], v[0:1] op_sel_hi:[1,0]
	v_pk_mul_f32 v[48:49], v[48:49], v[0:1] op_sel_hi:[1,0]
	v_pk_mul_f32 v[46:47], v[46:47], v[0:1] op_sel_hi:[1,0]
	v_cvt_pk_bf16_f32 v96, v97, v109
	v_cvt_pk_bf16_f32 v97, v99, v111
	v_cvt_pk_bf16_f32 v98, v113, v115
	v_cvt_pk_bf16_f32 v99, v119, v121
	v_pk_add_f32 v[100:101], v[114:115], v[100:101]
	s_setprio 1
	s_waitcnt lgkmcnt(0)
	v_mfma_f32_16x16x32_bf16 v[50:53], v[14:17], v[82:85], v[50:53]
	v_pk_add_f32 v[100:101], v[118:119], v[100:101]
	v_pk_add_f32 v[100:101], v[120:121], v[100:101]
	v_mfma_f32_16x16x32_bf16 v[54:57], v[10:13], v[82:85], v[54:57]
	v_fma_f32 v88, v88, v122, v100
	v_fma_f32 v89, v89, v123, v101
	v_mfma_f32_16x16x32_bf16 v[58:61], v[6:9], v[82:85], v[58:61]
	v_mfma_f32_16x16x32_bf16 v[62:65], v[2:5], v[82:85], v[62:65]
	v_mfma_f32_16x16x32_bf16 v[34:37], v[14:17], v[96:99], v[34:37]
	v_mfma_f32_16x16x32_bf16 v[38:41], v[10:13], v[96:99], v[38:41]
	v_mfma_f32_16x16x32_bf16 v[42:45], v[6:9], v[96:99], v[42:45]
	v_mfma_f32_16x16x32_bf16 v[46:49], v[2:5], v[96:99], v[46:49]
	s_setprio 0
	v_mov_b32_e32 v95, v117
	v_mov_b32_e32 v82, v81
	s_branch .LBB0_333

; #define LAS __attribute__((address_space(3)))
; template <int MODE> ...
;     ...
;             if (MODE == 1) { const int ks = ktok0 + 64 * t + 32 * hf;
;                 if (ks + 31 < qtok0 - 128 || ks > qtok0 + 31 + 128) continue; }
;             bf16x8 kf[2][2][2];
; #pragma unroll
;             for (int jj = 0; jj < 2; ++jj)
; #pragma unroll
;                 for (int kt = 0; kt < 2; ++kt)
; #pragma unroll
;                     for (int ks = 0; ks < 2; ++ks) kf[jj][kt][ks] = *(const LAS bf16x8*)(Sl + kad[jj][ks] + (32 * hf + 16 * kt) * 128);
;             f32x4 bb[2][2];
; #pragma unroll
;             for (int jj = 0; jj < 2; ++jj) { const LAS f32x4* bl = bcp + ((MODE == 0) ? (dr0 + t - act0) * 8 : 16 * t + 8 * hf) + bofs[jj];
; #pragma unroll
;                 for (int kt = 0; kt < 2; ++kt) bb[jj][kt] = bl[4 * kt]; }
;             s16x4 vlo[2][4], vhi[2][4];
; #pragma unroll
;             for (int jj = 0; jj < 2; ++jj)
; #pragma unroll
;                 for (int dt = 0; dt < 4; ++dt) { const LAS unsigned char* vp = Sl + vad[jj] + (32 * hf) * 128 + ((dt ^ sv) << 5);
;                     vlo[jj][dt] = __builtin_bit_cast(s16x4, __builtin_amdgcn_ds_read_tr16_b64_v4i16((LAS s16x4*)(vp)));
;                     vhi[jj][dt] = __builtin_bit_cast(s16x4, __builtin_amdgcn_ds_read_tr16_b64_v4i16((LAS s16x4*)(vp + 2048))); }
;             __builtin_amdgcn_sched_barrier(0);
;             f32x4 s[2][2];
; #pragma unroll
;             for (int jj = 0; jj < 2; ++jj)
; #pragma unroll
;                 for (int kt = 0; kt < 2; ++kt) { f32x4 a = (MODE == 0) ? bb[jj][kt] + mneg[jj][kt] : bb[jj][kt];
;                     a = __builtin_amdgcn_mfma_f32_16x16x32_bf16(kf[jj][kt][0], qf[jj][0], a, 0, 0, 0);
;                     s[jj][kt] = __builtin_amdgcn_mfma_f32_16x16x32_bf16(kf[jj][kt][1], qf[jj][1], a, 0, 0, 0); }
;             u32x4 pw[2];
; #pragma unroll
;             for (int jj = 0; jj < 2; ++jj) {
;                 const float tm = vmax3(vmax3(s[jj][0][0], s[jj][0][1], s[jj][0][2]), vmax3(s[jj][0][3], s[jj][1][0], s[jj][1][1]), vmax3(s[jj][1][2], s[jj][1][3], s[jj][1][3]));
;                 const float mn = quad_max3(mrun[jj], tm);
;                 const float alpha = __builtin_amdgcn_exp2f(mrun[jj] - mn);
;                 mrun[jj] = mn;
;                 float rsum = 0.f;
; #pragma unroll
;                 for (int kt = 0; kt < 2; ++kt)
; #pragma unroll
.LBB0_356:
	v_lshl_add_u64 v[6:7], v[66:67], 1, s[38:39]
	global_load_dwordx4 v[2:5], v[6:7], off
	global_load_dwordx4 v[10:13], v[6:7], off offset:64
	v_add_co_u32_e32 v6, vcc, 0x12000, v6
	s_cmp_lt_i32 s5, 1
	s_nop 0
	v_addc_co_u32_e32 v7, vcc, 0, v7, vcc
	global_load_dwordx4 v[14:17], v[6:7], off
	s_nop 0
	global_load_dwordx4 v[6:9], v[6:7], off offset:64
	s_cbranch_scc1 .LBB0_361
	s_mul_i32 s0, s22, 0x600
	s_add_i32 s27, s0, 0
	s_add_i32 s0, s26, s86
	s_mul_hi_i32 s14, s0, 0x55555556
	s_lshr_b32 s15, s14, 31
	s_add_i32 s14, s14, s15
	s_mul_i32 s14, s14, 3
	s_sub_i32 s0, s0, s14
	s_lshl_b32 s30, s26, 6
	s_lshl_b32 s0, s0, 14
	s_add_i32 s14, s30, s24
	s_add_i32 s27, s27, 0x10000
	s_add_i32 s0, s0, 0
	s_lshl_b32 s26, s26, 8
	s_or_b32 s15, s14, 31
	s_add_i32 s31, s25, 0xffffff80
	s_cmp_lt_i32 s15, s31
	s_cselect_b64 s[38:39], -1, 0
	s_addk_i32 s25, 0x9f
	s_cmp_gt_i32 s14, s25
	s_cselect_b64 s[40:41], -1, 0
	s_or_b64 s[38:39], s[38:39], s[40:41]
	v_add_u32_e32 v100, s0, v70
	v_add_u32_e32 v99, s0, v71
	v_add3_u32 v66, v72, v73, s0
	s_movk_i32 s0, 0x60
	s_and_b64 vcc, exec, s[38:39]
	v_add_u32_e32 v98, v66, v74
	v_xad_u32 v97, v74, 32, v66
	v_xad_u32 v0, v74, 64, v66
	v_xad_u32 v96, v74, s0, v66
	s_cbranch_vccnz .LBB0_359
	s_add_i32 s0, s27, s26
	v_lshl_add_u32 v66, v93, 4, s0
	ds_read_b128 v[102:105], v100
	ds_read_b128 v[106:109], v100 offset:2048
	ds_read_b128 v[110:113], v99
	ds_read_b128 v[118:121], v99 offset:2048
	ds_read_b128 v[122:125], v66
	ds_read_b128 v[126:129], v66 offset:64
	v_lshl_add_u32 v66, v94, 4, s0
	ds_read_b128 v[130:133], v66
	ds_read_b128 v[134:137], v66 offset:64
	ds_read_b64_tr_b16 v[78:79], v98 offset:8192
	ds_read_b64_tr_b16 v[80:81], v98 offset:10240
	ds_read_b64_tr_b16 v[74:75], v97 offset:8192
	ds_read_b64_tr_b16 v[76:77], v97 offset:10240
	ds_read_b64_tr_b16 v[70:71], v0 offset:8192
	ds_read_b64_tr_b16 v[72:73], v0 offset:10240
	ds_read_b64_tr_b16 v[66:67], v96 offset:8192
	ds_read_b64_tr_b16 v[68:69], v96 offset:10240
	s_waitcnt lgkmcnt(11)
	v_mfma_f32_16x16x32_bf16 v[122:125], v[102:105], v[30:33], v[122:125]
	s_waitcnt lgkmcnt(10)
	v_mfma_f32_16x16x32_bf16 v[126:129], v[106:109], v[30:33], v[126:129]
	s_waitcnt lgkmcnt(9)
	v_mfma_f32_16x16x32_bf16 v[102:105], v[102:105], v[22:25], v[130:133]
	s_waitcnt lgkmcnt(8)
	v_mfma_f32_16x16x32_bf16 v[106:109], v[106:109], v[22:25], v[134:137]
	v_mfma_f32_16x16x32_bf16 v[102:105], v[110:113], v[18:21], v[102:105]
	v_mfma_f32_16x16x32_bf16 v[106:109], v[118:121], v[18:21], v[106:109]
	v_mfma_f32_16x16x32_bf16 v[122:125], v[110:113], v[26:29], v[122:125]
	s_nop 5
	v_maximum3_f32 v111, v102, v103, v104
	v_maximum3_f32 v113, v105, v106, v107
	v_maximum3_f32 v115, v108, v109, v109
	v_mfma_f32_16x16x32_bf16 v[126:129], v[118:121], v[26:29], v[126:129]
	v_maximum3_f32 v111, v111, v113, v115
	v_maximum3_f32 v83, v122, v123, v124
	v_mov_b32_e32 v113, v111
	s_nop 1
	v_permlane16_swap_b32_e32 v111, v113
	v_maximum3_f32 v111, v111, v113, v113
	s_nop 0
	v_maximum3_f32 v84, v125, v126, v127
	v_maximum3_f32 v85, v128, v129, v129
	v_maximum3_f32 v83, v83, v84, v85
	v_mov_b32_e32 v84, v83
	s_nop 1
	v_permlane16_swap_b32_e32 v83, v84
	v_maximum3_f32 v83, v83, v84, v84
	v_mov_b32_e32 v113, v111
	v_mov_b32_e32 v84, v83
	s_nop 0
	v_permlane32_swap_b32_e32 v111, v113
	v_permlane32_swap_b32_e32 v83, v84
	v_maximum3_f32 v117, v95, v111, v113
	v_maximum3_f32 v101, v82, v83, v84
	v_sub_f32_e32 v102, v102, v117
	v_sub_f32_e32 v83, v122, v101
	v_exp_f32_e32 v111, v102
	v_sub_f32_e32 v102, v103, v117
	v_exp_f32_e32 v110, v83
	v_sub_f32_e32 v83, v123, v101
	v_exp_f32_e32 v113, v102
	v_sub_f32_e32 v102, v104, v117
	v_exp_f32_e32 v112, v83
	v_sub_f32_e32 v83, v124, v101
	v_exp_f32_e32 v115, v102
	v_sub_f32_e32 v102, v105, v117
	v_exp_f32_e32 v114, v83
	v_sub_f32_e32 v83, v125, v101
	v_exp_f32_e32 v119, v102
	v_sub_f32_e32 v102, v106, v117
	v_exp_f32_e32 v118, v83
	v_sub_f32_e32 v83, v126, v101
	v_exp_f32_e32 v121, v102
	v_sub_f32_e32 v102, v107, v117
	v_sub_f32_e32 v82, v82, v101
	v_exp_f32_e32 v120, v83
	v_sub_f32_e32 v83, v127, v101
	v_exp_f32_e32 v123, v102
	v_sub_f32_e32 v102, v108, v117
	v_exp_f32_e32 v122, v83
	v_sub_f32_e32 v83, v128, v101
	v_exp_f32_e32 v128, v82
	v_pk_add_f32 v[130:131], v[110:111], 0 op_sel_hi:[1,0]
	v_exp_f32_e32 v125, v102
	v_sub_f32_e32 v102, v109, v117
	v_exp_f32_e32 v127, v102
	v_pk_add_f32 v[102:103], v[112:113], v[130:131]
	v_exp_f32_e32 v124, v83
	v_sub_f32_e32 v83, v129, v101
	v_pk_add_f32 v[102:103], v[114:115], v[102:103]
	v_exp_f32_e32 v126, v83
	v_sub_f32_e32 v95, v95, v117
	v_pk_add_f32 v[102:103], v[118:119], v[102:103]
	v_pk_mul_f32 v[52:53], v[52:53], v[128:129] op_sel_hi:[1,0]
	v_pk_mul_f32 v[50:51], v[50:51], v[128:129] op_sel_hi:[1,0]
	v_pk_mul_f32 v[56:57], v[56:57], v[128:129] op_sel_hi:[1,0]
	v_pk_mul_f32 v[54:55], v[54:55], v[128:129] op_sel_hi:[1,0]
	v_pk_mul_f32 v[60:61], v[60:61], v[128:129] op_sel_hi:[1,0]
	v_pk_mul_f32 v[58:59], v[58:59], v[128:129] op_sel_hi:[1,0]
	v_pk_mul_f32 v[64:65], v[64:65], v[128:129] op_sel_hi:[1,0]
	v_pk_mul_f32 v[62:63], v[62:63], v[128:129] op_sel_hi:[1,0]
	v_exp_f32_e32 v129, v95
	v_pk_add_f32 v[102:103], v[120:121], v[102:103]
	v_cvt_pk_bf16_f32 v82, v110, v112
	v_pk_add_f32 v[102:103], v[122:123], v[102:103]
	v_cvt_pk_bf16_f32 v83, v114, v118
	v_pk_add_f32 v[102:103], v[124:125], v[102:103]
	v_cvt_pk_bf16_f32 v84, v120, v122
	v_pk_add_f32 v[102:103], v[126:127], v[102:103]
	v_cvt_pk_bf16_f32 v85, v124, v126
	v_pk_fma_f32 v[88:89], v[88:89], v[128:129], v[102:103]
	v_mov_b32_e32 v102, v129
	v_pk_mul_f32 v[36:37], v[36:37], v[102:103] op_sel_hi:[1,0]
	v_pk_mul_f32 v[34:35], v[34:35], v[102:103] op_sel_hi:[1,0]
	v_pk_mul_f32 v[40:41], v[40:41], v[102:103] op_sel_hi:[1,0]
	v_pk_mul_f32 v[38:39], v[38:39], v[102:103] op_sel_hi:[1,0]
	v_pk_mul_f32 v[44:45], v[44:45], v[102:103] op_sel_hi:[1,0]
	v_pk_mul_f32 v[42:43], v[42:43], v[102:103] op_sel_hi:[1,0]
	v_pk_mul_f32 v[48:49], v[48:49], v[102:103] op_sel_hi:[1,0]
	v_pk_mul_f32 v[46:47], v[46:47], v[102:103] op_sel_hi:[1,0]
	v_cvt_pk_bf16_f32 v102, v111, v113
	v_cvt_pk_bf16_f32 v103, v115, v119
	v_cvt_pk_bf16_f32 v104, v121, v123
	v_cvt_pk_bf16_f32 v105, v125, v127
	s_setprio 1
	s_waitcnt lgkmcnt(0)
	v_mfma_f32_16x16x32_bf16 v[50:53], v[78:81], v[82:85], v[50:53]
	v_mfma_f32_16x16x32_bf16 v[54:57], v[74:77], v[82:85], v[54:57]
	v_mfma_f32_16x16x32_bf16 v[58:61], v[70:73], v[82:85], v[58:61]
	v_mfma_f32_16x16x32_bf16 v[62:65], v[66:69], v[82:85], v[62:65]
	v_mfma_f32_16x16x32_bf16 v[34:37], v[78:81], v[102:105], v[34:37]
	v_mfma_f32_16x16x32_bf16 v[38:41], v[74:77], v[102:105], v[38:41]
	v_mfma_f32_16x16x32_bf16 v[42:45], v[70:73], v[102:105], v[42:45]
	v_mfma_f32_16x16x32_bf16 v[46:49], v[66:69], v[102:105], v[46:49]
	s_setprio 0
	v_mov_b32_e32 v82, v101
	v_mov_b32_e32 v95, v117
; #define LAS __attribute__((address_space(3)))
; template <int MODE> ...
;     ...
;             if (MODE == 1) { const int ks = ktok0 + 64 * t + 32 * hf;
;                 if (ks + 31 < qtok0 - 128 || ks > qtok0 + 31 + 128) continue; }
;             bf16x8 kf[2][2][2];
; #pragma unroll
;             for (int jj = 0; jj < 2; ++jj)
; #pragma unroll
;                 for (int kt = 0; kt < 2; ++kt)
; #pragma unroll
;                     for (int ks = 0; ks < 2; ++ks) kf[jj][kt][ks] = *(const LAS bf16x8*)(Sl + kad[jj][ks] + (32 * hf + 16 * kt) * 128);
;             f32x4 bb[2][2];
; #pragma unroll
;             for (int jj = 0; jj < 2; ++jj) { const LAS f32x4* bl = bcp + ((MODE == 0) ? (dr0 + t - act0) * 8 : 16 * t + 8 * hf) + bofs[jj];
; #pragma unroll
;                 for (int kt = 0; kt < 2; ++kt) bb[jj][kt] = bl[4 * kt]; }
;             s16x4 vlo[2][4], vhi[2][4];
; #pragma unroll
;             for (int jj = 0; jj < 2; ++jj)
; #pragma unroll
;                 for (int dt = 0; dt < 4; ++dt) { const LAS unsigned char* vp = Sl + vad[jj] + (32 * hf) * 128 + ((dt ^ sv) << 5);
;                     vlo[jj][dt] = __builtin_bit_cast(s16x4, __builtin_amdgcn_ds_read_tr16_b64_v4i16((LAS s16x4*)(vp)));
;                     vhi[jj][dt] = __builtin_bit_cast(s16x4, __builtin_amdgcn_ds_read_tr16_b64_v4i16((LAS s16x4*)(vp + 2048))); }
;             __builtin_amdgcn_sched_barrier(0);
;             f32x4 s[2][2];
; #pragma unroll
;             for (int jj = 0; jj < 2; ++jj)
; #pragma unroll
;                 for (int kt = 0; kt < 2; ++kt) { f32x4 a = (MODE == 0) ? bb[jj][kt] + mneg[jj][kt] : bb[jj][kt];
;                     a = __builtin_amdgcn_mfma_f32_16x16x32_bf16(kf[jj][kt][0], qf[jj][0], a, 0, 0, 0);
;                     s[jj][kt] = __builtin_amdgcn_mfma_f32_16x16x32_bf16(kf[jj][kt][1], qf[jj][1], a, 0, 0, 0); }
;             u32x4 pw[2];
; #pragma unroll
;             for (int jj = 0; jj < 2; ++jj) {
;                 const float tm = vmax3(vmax3(s[jj][0][0], s[jj][0][1], s[jj][0][2]), vmax3(s[jj][0][3], s[jj][1][0], s[jj][1][1]), vmax3(s[jj][1][2], s[jj][1][3], s[jj][1][3]));
;                 const float mn = quad_max3(mrun[jj], tm);
;                 const float alpha = __builtin_amdgcn_exp2f(mrun[jj] - mn);
;                 mrun[jj] = mn;
;                 float rsum = 0.f;
; #pragma unroll
;                 for (int kt = 0; kt < 2; ++kt)
; #pragma unroll
.LBB0_359:
	s_or_b32 s0, s30, 32
	s_add_i32 s0, s0, s24
	s_or_b32 s14, s0, 31
	s_cmp_lt_i32 s14, s31
	s_cselect_b64 s[30:31], -1, 0
	s_cmp_gt_i32 s0, s25
	s_cselect_b64 s[24:25], -1, 0
	s_or_b64 s[24:25], s[30:31], s[24:25]
	s_and_b64 vcc, exec, s[24:25]
	s_cbranch_vccnz .LBB0_361
	s_add_i32 s27, s27, s26
	v_lshl_add_u32 v83, v93, 4, s27
	ds_read_b128 v[66:69], v100 offset:4096
	ds_read_b128 v[70:73], v100 offset:6144
	ds_read_b128 v[74:77], v99 offset:4096
	ds_read_b128 v[78:81], v99 offset:6144
	ds_read_b128 v[100:103], v83 offset:128
	ds_read_b128 v[104:107], v83 offset:192
	v_lshl_add_u32 v83, v94, 4, s27
	ds_read_b128 v[108:111], v83 offset:128
	ds_read_b128 v[112:115], v83 offset:192
	ds_read_b64_tr_b16 v[118:119], v98 offset:12288
	ds_read_b64_tr_b16 v[120:121], v98 offset:14336
	ds_read_b64_tr_b16 v[122:123], v97 offset:12288
	ds_read_b64_tr_b16 v[124:125], v97 offset:14336
	ds_read_b64_tr_b16 v[126:127], v0 offset:12288
	ds_read_b64_tr_b16 v[128:129], v0 offset:14336
	ds_read_b64_tr_b16 v[130:131], v96 offset:12288
	ds_read_b64_tr_b16 v[132:133], v96 offset:14336
	s_waitcnt lgkmcnt(11)
	v_mfma_f32_16x16x32_bf16 v[96:99], v[66:69], v[30:33], v[100:103]
	s_waitcnt lgkmcnt(10)
	v_mfma_f32_16x16x32_bf16 v[30:33], v[70:73], v[30:33], v[104:107]
	v_mfma_f32_16x16x32_bf16 v[96:99], v[74:77], v[26:29], v[96:99]
	v_mfma_f32_16x16x32_bf16 v[26:29], v[78:81], v[26:29], v[30:33]
	s_nop 6
	v_maximum3_f32 v0, v96, v97, v98
	v_maximum3_f32 v30, v99, v26, v27
	v_maximum3_f32 v31, v28, v29, v29
	v_maximum3_f32 v0, v0, v30, v31
	v_mov_b32_e32 v30, v0
	s_nop 1
	v_permlane16_swap_b32_e32 v0, v30
	v_maximum3_f32 v0, v0, v30, v30
	v_mov_b32_e32 v30, v0
	s_nop 1
	v_permlane32_swap_b32_e32 v0, v30
	v_maximum3_f32 v0, v82, v0, v30
	s_waitcnt lgkmcnt(9)
	v_mfma_f32_16x16x32_bf16 v[30:33], v[66:69], v[22:25], v[108:111]
	v_sub_f32_e32 v83, v82, v0
	v_sub_f32_e32 v66, v97, v0
	v_exp_f32_e32 v84, v66
	s_waitcnt lgkmcnt(8)
	v_mfma_f32_16x16x32_bf16 v[22:25], v[70:73], v[22:25], v[112:115]
	v_sub_f32_e32 v66, v98, v0
	v_sub_f32_e32 v82, v96, v0
	v_sub_f32_e32 v26, v26, v0
	v_mfma_f32_16x16x32_bf16 v[30:33], v[74:77], v[18:21], v[30:33]
	v_exp_f32_e32 v74, v66
	v_sub_f32_e32 v66, v99, v0
	v_exp_f32_e32 v82, v82
	v_mfma_f32_16x16x32_bf16 v[18:21], v[78:81], v[18:21], v[22:25]
	v_exp_f32_e32 v78, v83
	v_exp_f32_e32 v70, v66
	v_exp_f32_e32 v72, v26
	v_sub_f32_e32 v22, v27, v0
	v_exp_f32_e32 v76, v22
	v_sub_f32_e32 v22, v28, v0
	v_sub_f32_e32 v0, v29, v0
	v_exp_f32_e32 v80, v22
	v_exp_f32_e32 v94, v0
	v_pk_mul_f32 v[22:23], v[50:51], v[78:79] op_sel_hi:[1,0]
	v_maximum3_f32 v0, v30, v31, v32
	v_maximum3_f32 v50, v33, v18, v19
	v_maximum3_f32 v51, v20, v21, v21
	v_maximum3_f32 v0, v0, v50, v51
	v_mov_b32_e32 v50, v0
	s_nop 1
	v_permlane16_swap_b32_e32 v0, v50
	v_maximum3_f32 v0, v0, v50, v50
	v_mov_b32_e32 v50, v0
	s_nop 1
	v_permlane32_swap_b32_e32 v0, v50
	v_maximum3_f32 v0, v95, v0, v50
	v_sub_f32_e32 v30, v30, v0
	v_exp_f32_e32 v83, v30
	v_sub_f32_e32 v30, v31, v0
	v_exp_f32_e32 v85, v30
	v_sub_f32_e32 v30, v32, v0
	v_sub_f32_e32 v18, v18, v0
	v_exp_f32_e32 v75, v30
	v_sub_f32_e32 v30, v33, v0
	v_exp_f32_e32 v73, v18
	v_sub_f32_e32 v18, v19, v0
	v_sub_f32_e32 v50, v95, v0
	v_exp_f32_e32 v71, v30
	v_exp_f32_e32 v77, v18
	v_sub_f32_e32 v18, v20, v0
	v_pk_mul_f32 v[24:25], v[52:53], v[78:79] op_sel_hi:[1,0]
	v_pk_mul_f32 v[28:29], v[56:57], v[78:79] op_sel_hi:[1,0]
	v_pk_mul_f32 v[26:27], v[54:55], v[78:79] op_sel_hi:[1,0]
	v_pk_mul_f32 v[60:61], v[60:61], v[78:79] op_sel_hi:[1,0]
	v_pk_mul_f32 v[58:59], v[58:59], v[78:79] op_sel_hi:[1,0]
	v_pk_mul_f32 v[64:65], v[64:65], v[78:79] op_sel_hi:[1,0]
	v_pk_mul_f32 v[62:63], v[62:63], v[78:79] op_sel_hi:[1,0]
	v_exp_f32_e32 v81, v18
	v_sub_f32_e32 v0, v21, v0
	v_exp_f32_e32 v79, v50
	v_pk_add_f32 v[18:19], v[82:83], 0 op_sel_hi:[1,0]
	v_exp_f32_e32 v95, v0
	v_pk_add_f32 v[18:19], v[84:85], v[18:19]
	v_cvt_pk_bf16_f32 v66, v82, v84
	v_pk_add_f32 v[18:19], v[74:75], v[18:19]
	v_cvt_pk_bf16_f32 v67, v74, v70
	v_pk_add_f32 v[18:19], v[70:71], v[18:19]
	v_cvt_pk_bf16_f32 v68, v72, v76
	v_cvt_pk_bf16_f32 v69, v80, v94
	v_pk_add_f32 v[18:19], v[72:73], v[18:19]
	v_mov_b32_e32 v0, v79
	s_setprio 1
	s_waitcnt lgkmcnt(0)
	v_mfma_f32_16x16x32_bf16 v[50:53], v[118:121], v[66:69], v[22:25]
	v_pk_mul_f32 v[20:21], v[36:37], v[0:1] op_sel_hi:[1,0]
	v_mfma_f32_16x16x32_bf16 v[54:57], v[122:125], v[66:69], v[26:29]
	v_cvt_pk_bf16_f32 v22, v83, v85
	v_cvt_pk_bf16_f32 v23, v75, v71
	v_cvt_pk_bf16_f32 v24, v73, v77
	v_pk_add_f32 v[26:27], v[76:77], v[18:19]
	v_pk_mul_f32 v[18:19], v[34:35], v[0:1] op_sel_hi:[1,0]
	v_cvt_pk_bf16_f32 v25, v81, v95
	v_mfma_f32_16x16x32_bf16 v[58:61], v[126:129], v[66:69], v[58:61]
	v_pk_add_f32 v[26:27], v[80:81], v[26:27]
	v_pk_add_f32 v[26:27], v[94:95], v[26:27]
	v_mfma_f32_16x16x32_bf16 v[34:37], v[118:121], v[22:25], v[18:21]
	v_fma_f32 v88, v88, v78, v26
	v_fma_f32 v89, v89, v79, v27
	s_nop 0
	v_pk_mul_f32 v[20:21], v[40:41], v[0:1] op_sel_hi:[1,0]
	v_pk_mul_f32 v[18:19], v[38:39], v[0:1] op_sel_hi:[1,0]
	v_mfma_f32_16x16x32_bf16 v[62:65], v[130:133], v[66:69], v[62:65]
	v_mfma_f32_16x16x32_bf16 v[38:41], v[122:125], v[22:25], v[18:21]
	s_setprio 0
	s_nop 2
	v_pk_mul_f32 v[20:21], v[44:45], v[0:1] op_sel_hi:[1,0]
	v_pk_mul_f32 v[18:19], v[42:43], v[0:1] op_sel_hi:[1,0]
	s_nop 1
	v_mfma_f32_16x16x32_bf16 v[42:45], v[126:129], v[22:25], v[18:21]
	s_nop 2
	v_pk_mul_f32 v[20:21], v[48:49], v[0:1] op_sel_hi:[1,0]
	v_pk_mul_f32 v[18:19], v[46:47], v[0:1] op_sel_hi:[1,0]
	s_nop 1
	v_mfma_f32_16x16x32_bf16 v[46:49], v[130:133], v[22:25], v[18:21]
